# K-loop first iteration peeled in six GEMM phases: first MFMA of each accumulator takes C=0, the 127 accumulator-zeroing moves per tile removed
# speedup vs baseline: 1.0096x; 1.0096x over previous
; #define PG8_STAGE(bufoff, gbase, voff) do { _Pragma("unroll") for (int _i = 0; _i < 2; ++_i) \
;         __builtin_amdgcn_global_load_lds((const unsigned*)((const char*)(gbase) + (voff)[_i]), (LAS unsigned*)(lds + (bufoff) + ldsw + _i * 8192), 16, 0, 0); } while (0)
; #define PG8_LDA(dst, b, h) do { _Pragma("unroll") for (int m = 0; m < 4; ++m) _Pragma("unroll") for (int k = 0; k < 2; ++k) dst[m][k] = *(const LAS bf16x8*)(lds + PG8_SA(b, h) + aoff + m * 2048 + k * 1024); } while (0)
; #define PG8_LDB(dst, b, h) do { _Pragma("unroll") for (int n = 0; n < 2; ++n) _Pragma("unroll") for (int k = 0; k < 2; ++k) dst[n][k] = *(const LAS bf16x8*)(lds + PG8_SB(b, h) + boff + n * 2048 + k * 1024); } while (0)
; #define PG8_MMA(ai, bj, At, Bt) do { __builtin_amdgcn_s_setprio(1); _Pragma("unroll") for (int m = 0; m < 4; ++m) _Pragma("unroll") for (int n = 0; n < 2; ++n) _Pragma("unroll") for (int k = 0; k < 2; ++k) \
;         acc[ai][bj][m][n] = __builtin_amdgcn_mfma_f32_16x16x32_bf16(Bt[n][k], At[m][k], acc[ai][bj][m][n], 0, 0, 0); __builtin_amdgcn_s_setprio(0); } while (0)
; #define PG8_WAIT_V(n) asm volatile("s_waitcnt vmcnt(" #n ")" ::: "memory")
; #define PG8_WAIT_L(n) asm volatile("s_waitcnt lgkmcnt(" #n ")" ::: "memory")
; #define PG8_BAR __builtin_amdgcn_s_barrier()
; #define PG8_SCHED __builtin_amdgcn_sched_barrier(0)
; template <class Sched, class Epi, bool ALIGN_EPI, bool SP2>
; __device__ __forceinline__ void gemm_phase(LAS unsigned char* lds, const int K, const int lda, const int ldb, const Sched& S, const Epi& E) {
;     ...
;     f32x4 acc[2][2][4][2];
; #pragma unroll
;     for (int a = 0; a < 2; ++a)
; #pragma unroll
;         for (int b = 0; b < 2; ++b)
; #pragma unroll
;             for (int m = 0; m < 4; ++m)
; #pragma unroll
;                 for (int n = 0; n < 2; ++n) acc[a][b][m][n] = (f32x4){0.f, 0.f, 0.f, 0.f};
;     ...
;             PG8_LDB(B0, 0, 0); PG8_LDB(B1, 0, 1); PG8_SCHED; PG8_LDA(At, 0, 0); PG8_STAGE(PG8_SA(1, 1), a1 + hstepA, voffA);
;             PG8_WAIT_V(8); PG8_WAIT_L(0); PG8_BAR; PG8_MMA(0, 0, At, B0); PG8_MMA(0, 1, At, B1); PG8_BAR; PG8_SCHED;
;             PG8_LDA(At, 0, 1); PG8_STAGE(PG8_SB(0, 0), b2, voffB); PG8_STAGE(PG8_SB(0, 1), b2 + hstepB, voffB); PG8_STAGE(PG8_SA(0, 0), a2, voffA);
;             PG8_WAIT_V(8); PG8_WAIT_L(0); PG8_BAR; PG8_MMA(1, 0, At, B0); PG8_MMA(1, 1, At, B1); PG8_BAR; PG8_SCHED;
.LBB0_154:
	s_add_u32 s20, s20, 0x80080
	s_addc_u32 s21, s21, 0
	s_add_u32 s13, s22, 0x100
	v_mov_b32_e32 v0, 0
	s_addc_u32 s74, s23, 0
	s_mov_b32 s75, -2
	v_readlane_b32 s98, v255, 13
	s_nop 4
	s_cmp_gt_u32 s98, 3
	s_cbranch_scc1 .Lprio_skip_155
	s_setprio 1
.Lprio_skip_155:
	ds_read_b128 v[140:143], v147
	ds_read_b128 v[150:153], v147 offset:1024
	ds_read_b128 v[154:157], v147 offset:2048
	ds_read_b128 v[158:161], v147 offset:3072
	ds_read_b128 v[162:165], v148
	ds_read_b128 v[166:169], v148 offset:1024
	ds_read_b128 v[170:173], v148 offset:2048
	ds_read_b128 v[180:183], v148 offset:3072
	s_add_u32 s22, s20, 0xfff80080
	s_addc_u32 s23, s21, -1
	s_cmp_eq_u32 s75, 28
	s_cselect_b32 s25, s15, s23
	s_cselect_b32 s24, s14, s22
	s_cselect_b32 s23, s17, s74
	s_cselect_b32 s22, s16, s13
	s_add_i32 m0, s3, 0xc000
	ds_read_b128 v[184:187], v149
	ds_read_b128 v[188:191], v149 offset:1024
	ds_read_b128 v[192:195], v149 offset:2048
	ds_read_b128 v[196:199], v149 offset:3072
	ds_read_b128 v[200:203], v149 offset:4096
	ds_read_b128 v[204:207], v149 offset:5120
	ds_read_b128 v[208:211], v149 offset:6144
	ds_read_b128 v[212:215], v149 offset:7168
	global_load_lds_dwordx4 v136, s[20:21]
	s_add_i32 m0, s3, 0xe000
	s_nop 0
	global_load_lds_dwordx4 v138, s[20:21]
	s_waitcnt vmcnt(8) lgkmcnt(0)
	s_barrier
	v_mfma_f32_16x16x32_bf16 v[124:127], v[140:143], v[184:187], 0
	v_mfma_f32_16x16x32_bf16 v[120:123], v[154:157], v[184:187], 0
	v_mfma_f32_16x16x32_bf16 v[108:111], v[140:143], v[192:195], 0
	v_mfma_f32_16x16x32_bf16 v[104:107], v[154:157], v[192:195], 0
	v_mfma_f32_16x16x32_bf16 v[92:95], v[140:143], v[200:203], 0
	v_mfma_f32_16x16x32_bf16 v[88:91], v[154:157], v[200:203], 0
	v_mfma_f32_16x16x32_bf16 v[76:79], v[140:143], v[208:211], 0
	v_mfma_f32_16x16x32_bf16 v[72:75], v[154:157], v[208:211], 0
	v_mfma_f32_16x16x32_bf16 v[124:127], v[150:153], v[188:191], v[124:127]
	v_mfma_f32_16x16x32_bf16 v[120:123], v[158:161], v[188:191], v[120:123]
	v_mfma_f32_16x16x32_bf16 v[108:111], v[150:153], v[196:199], v[108:111]
	v_mfma_f32_16x16x32_bf16 v[104:107], v[158:161], v[196:199], v[104:107]
	v_mfma_f32_16x16x32_bf16 v[92:95], v[150:153], v[204:207], v[92:95]
	v_mfma_f32_16x16x32_bf16 v[88:91], v[158:161], v[204:207], v[88:91]
	v_mfma_f32_16x16x32_bf16 v[76:79], v[150:153], v[212:215], v[76:79]
	v_mfma_f32_16x16x32_bf16 v[72:75], v[158:161], v[212:215], v[72:75]
	v_mfma_f32_16x16x32_bf16 v[116:119], v[162:165], v[184:187], 0
	v_mfma_f32_16x16x32_bf16 v[112:115], v[170:173], v[184:187], 0
	v_mfma_f32_16x16x32_bf16 v[100:103], v[162:165], v[192:195], 0
	v_mfma_f32_16x16x32_bf16 v[96:99], v[170:173], v[192:195], 0
	v_mfma_f32_16x16x32_bf16 v[84:87], v[162:165], v[200:203], 0
	v_mfma_f32_16x16x32_bf16 v[80:83], v[170:173], v[200:203], 0
	v_mfma_f32_16x16x32_bf16 v[68:71], v[162:165], v[208:211], 0
	v_mfma_f32_16x16x32_bf16 v[64:67], v[170:173], v[208:211], 0
	v_mfma_f32_16x16x32_bf16 v[116:119], v[166:169], v[188:191], v[116:119]
	v_mfma_f32_16x16x32_bf16 v[112:115], v[180:183], v[188:191], v[112:115]
	v_mfma_f32_16x16x32_bf16 v[100:103], v[166:169], v[196:199], v[100:103]
	v_mfma_f32_16x16x32_bf16 v[96:99], v[180:183], v[196:199], v[96:99]
	v_mfma_f32_16x16x32_bf16 v[84:87], v[166:169], v[204:207], v[84:87]
	v_mfma_f32_16x16x32_bf16 v[80:83], v[180:183], v[204:207], v[80:83]
	v_mfma_f32_16x16x32_bf16 v[68:71], v[166:169], v[212:215], v[68:71]
	v_mfma_f32_16x16x32_bf16 v[64:67], v[180:183], v[212:215], v[64:67]
	s_barrier
	s_add_i32 s78, s35, s2
	v_lshl_add_u64 v[174:175], s[22:23], 0, v[130:131]
	s_mov_b32 m0, s78
	ds_read_b128 v[184:187], v149 offset:16384
	ds_read_b128 v[188:191], v149 offset:17408
	ds_read_b128 v[192:195], v149 offset:18432
	ds_read_b128 v[196:199], v149 offset:19456
	ds_read_b128 v[200:203], v149 offset:20480
	ds_read_b128 v[204:207], v149 offset:21504
	ds_read_b128 v[208:211], v149 offset:22528
	ds_read_b128 v[212:215], v149 offset:23552
	global_load_lds_dwordx4 v[174:175], off
	s_add_i32 m0, s78, 0x2000
	s_add_u32 s78, s22, 0x80000
	v_lshl_add_u64 v[216:217], s[22:23], 0, v[134:135]
	s_addc_u32 s79, s23, 0
	s_add_i32 s84, s50, s2
	global_load_lds_dwordx4 v[216:217], off
	s_mov_b32 m0, s84
	v_lshl_add_u64 v[220:221], s[24:25], 0, v[132:133]
	global_load_lds_dwordx4 v130, s[78:79]
	s_add_i32 m0, s84, 0x2000
	s_nop 0
	global_load_lds_dwordx4 v134, s[78:79]
	v_lshl_add_u64 v[218:219], s[24:25], 0, v[128:129]
	s_mov_b32 m0, s3
	s_nop 0
	global_load_lds_dwordx4 v[218:219], off
	s_mov_b32 m0, s19
	s_nop 0
	global_load_lds_dwordx4 v[220:221], off
	s_waitcnt vmcnt(8) lgkmcnt(0)
	s_barrier
	v_mfma_f32_16x16x32_bf16 v[60:63], v[140:143], v[184:187], 0
	v_mfma_f32_16x16x32_bf16 v[56:59], v[154:157], v[184:187], 0
	v_mfma_f32_16x16x32_bf16 v[44:47], v[140:143], v[192:195], 0
	v_mfma_f32_16x16x32_bf16 v[40:43], v[154:157], v[192:195], 0
	v_mfma_f32_16x16x32_bf16 v[28:31], v[140:143], v[200:203], 0
	v_mfma_f32_16x16x32_bf16 v[24:27], v[154:157], v[200:203], 0
	v_mfma_f32_16x16x32_bf16 v[12:15], v[140:143], v[208:211], 0
	v_mfma_f32_16x16x32_bf16 v[8:11], v[154:157], v[208:211], 0
	v_mfma_f32_16x16x32_bf16 v[60:63], v[150:153], v[188:191], v[60:63]
	v_mfma_f32_16x16x32_bf16 v[56:59], v[158:161], v[188:191], v[56:59]
	v_mfma_f32_16x16x32_bf16 v[44:47], v[150:153], v[196:199], v[44:47]
	v_mfma_f32_16x16x32_bf16 v[40:43], v[158:161], v[196:199], v[40:43]
	v_mfma_f32_16x16x32_bf16 v[28:31], v[150:153], v[204:207], v[28:31]
	v_mfma_f32_16x16x32_bf16 v[24:27], v[158:161], v[204:207], v[24:27]
	v_mfma_f32_16x16x32_bf16 v[12:15], v[150:153], v[212:215], v[12:15]
	v_mfma_f32_16x16x32_bf16 v[8:11], v[158:161], v[212:215], v[8:11]
	v_mfma_f32_16x16x32_bf16 v[52:55], v[162:165], v[184:187], 0
	v_mfma_f32_16x16x32_bf16 v[48:51], v[170:173], v[184:187], 0
	v_mfma_f32_16x16x32_bf16 v[36:39], v[162:165], v[192:195], 0
	v_mfma_f32_16x16x32_bf16 v[32:35], v[170:173], v[192:195], 0
	v_mfma_f32_16x16x32_bf16 v[20:23], v[162:165], v[200:203], 0
	v_mfma_f32_16x16x32_bf16 v[16:19], v[170:173], v[200:203], 0
	v_mfma_f32_16x16x32_bf16 v[4:7], v[162:165], v[208:211], 0
	v_mfma_f32_16x16x32_bf16 v[0:3], v[170:173], v[208:211], 0
	v_mfma_f32_16x16x32_bf16 v[52:55], v[166:169], v[188:191], v[52:55]
	v_mfma_f32_16x16x32_bf16 v[48:51], v[180:183], v[188:191], v[48:51]
	v_mfma_f32_16x16x32_bf16 v[36:39], v[166:169], v[196:199], v[36:39]
	v_mfma_f32_16x16x32_bf16 v[32:35], v[180:183], v[196:199], v[32:35]
	v_mfma_f32_16x16x32_bf16 v[20:23], v[166:169], v[204:207], v[20:23]
	v_mfma_f32_16x16x32_bf16 v[16:19], v[180:183], v[204:207], v[16:19]
	v_mfma_f32_16x16x32_bf16 v[4:7], v[166:169], v[212:215], v[4:7]
	v_mfma_f32_16x16x32_bf16 v[0:3], v[180:183], v[212:215], v[0:3]
	s_barrier
; #define PG8_STAGE(bufoff, gbase, voff) do { _Pragma("unroll") for (int _i = 0; _i < 2; ++_i) \
;         __builtin_amdgcn_global_load_lds((const unsigned*)((const char*)(gbase) + (voff)[_i]), (LAS unsigned*)(lds + (bufoff) + ldsw + _i * 8192), 16, 0, 0); } while (0)
; #define PG8_LDA(dst, b, h) do { _Pragma("unroll") for (int m = 0; m < 4; ++m) _Pragma("unroll") for (int k = 0; k < 2; ++k) dst[m][k] = *(const LAS bf16x8*)(lds + PG8_SA(b, h) + aoff + m * 2048 + k * 1024); } while (0)
; #define PG8_LDB(dst, b, h) do { _Pragma("unroll") for (int n = 0; n < 2; ++n) _Pragma("unroll") for (int k = 0; k < 2; ++k) dst[n][k] = *(const LAS bf16x8*)(lds + PG8_SB(b, h) + boff + n * 2048 + k * 1024); } while (0)
; #define PG8_MMA(ai, bj, At, Bt) do { __builtin_amdgcn_s_setprio(1); _Pragma("unroll") for (int m = 0; m < 4; ++m) _Pragma("unroll") for (int n = 0; n < 2; ++n) _Pragma("unroll") for (int k = 0; k < 2; ++k) \
;         acc[ai][bj][m][n] = __builtin_amdgcn_mfma_f32_16x16x32_bf16(Bt[n][k], At[m][k], acc[ai][bj][m][n], 0, 0, 0); __builtin_amdgcn_s_setprio(0); } while (0)
; #define PG8_WAIT_V(n) asm volatile("s_waitcnt vmcnt(" #n ")" ::: "memory")
; #define PG8_WAIT_L(n) asm volatile("s_waitcnt lgkmcnt(" #n ")" ::: "memory")
; #define PG8_BAR __builtin_amdgcn_s_barrier()
; #define PG8_SCHED __builtin_amdgcn_sched_barrier(0)
; template <class Sched, class Epi, bool ALIGN_EPI, bool SP2>
; __device__ __forceinline__ void gemm_phase(LAS unsigned char* lds, const int K, const int lda, const int ldb, const Sched& S, const Epi& E) {
;     ...
;             PG8_LDB(B0, 1, 0); PG8_LDB(B1, 1, 1); PG8_SCHED; PG8_LDA(At, 1, 0); PG8_STAGE(PG8_SA(0, 1), a2 + hstepA, voffA);
;             PG8_WAIT_V(8); PG8_WAIT_L(0); PG8_BAR; PG8_MMA(0, 0, At, B0); PG8_MMA(0, 1, At, B1); PG8_BAR; PG8_SCHED;
;             PG8_LDA(At, 1, 1); PG8_STAGE(PG8_SB(1, 0), b3, voffB); PG8_STAGE(PG8_SB(1, 1), b3 + hstepB, voffB); PG8_STAGE(PG8_SA(1, 0), a3, voffA);
;             PG8_WAIT_V(8); PG8_WAIT_L(0); PG8_BAR; PG8_MMA(1, 0, At, B0); PG8_MMA(1, 1, At, B1); PG8_BAR; PG8_SCHED;
	s_add_i32 s78, 0, 0x18000
	s_add_i32 s79, 0, 0x1c000
	v_add_u32_e32 v158, s78, v145
	v_add_u32_e32 v177, s79, v145
	ds_read_b128 v[140:143], v158
	ds_read_b128 v[150:153], v158 offset:1024
	ds_read_b128 v[154:157], v158 offset:2048
	ds_read_b128 v[158:161], v158 offset:3072
	ds_read_b128 v[162:165], v177
	ds_read_b128 v[166:169], v177 offset:1024
	ds_read_b128 v[170:173], v177 offset:2048
	ds_read_b128 v[180:183], v177 offset:3072
	s_add_u32 s24, s24, 0x80000
	s_addc_u32 s25, s25, 0
	s_mov_b32 m0, s26
	ds_read_b128 v[184:187], v149 offset:32768
	ds_read_b128 v[188:191], v149 offset:33792
	ds_read_b128 v[192:195], v149 offset:34816
	ds_read_b128 v[196:199], v149 offset:35840
	ds_read_b128 v[200:203], v149 offset:36864
	ds_read_b128 v[204:207], v149 offset:37888
	ds_read_b128 v[208:211], v149 offset:38912
	ds_read_b128 v[212:215], v149 offset:39936
	global_load_lds_dwordx4 v128, s[24:25]
	s_mov_b32 m0, s27
	s_nop 0
	global_load_lds_dwordx4 v132, s[24:25]
	s_waitcnt vmcnt(8) lgkmcnt(0)
	s_barrier
	v_mfma_f32_16x16x32_bf16 v[124:127], v[140:143], v[184:187], v[124:127]
	v_mfma_f32_16x16x32_bf16 v[120:123], v[154:157], v[184:187], v[120:123]
	v_mfma_f32_16x16x32_bf16 v[108:111], v[140:143], v[192:195], v[108:111]
	v_mfma_f32_16x16x32_bf16 v[104:107], v[154:157], v[192:195], v[104:107]
	v_mfma_f32_16x16x32_bf16 v[92:95], v[140:143], v[200:203], v[92:95]
	v_mfma_f32_16x16x32_bf16 v[88:91], v[154:157], v[200:203], v[88:91]
	v_mfma_f32_16x16x32_bf16 v[76:79], v[140:143], v[208:211], v[76:79]
	v_mfma_f32_16x16x32_bf16 v[72:75], v[154:157], v[208:211], v[72:75]
	v_mfma_f32_16x16x32_bf16 v[124:127], v[150:153], v[188:191], v[124:127]
	v_mfma_f32_16x16x32_bf16 v[120:123], v[158:161], v[188:191], v[120:123]
	v_mfma_f32_16x16x32_bf16 v[108:111], v[150:153], v[196:199], v[108:111]
	v_mfma_f32_16x16x32_bf16 v[104:107], v[158:161], v[196:199], v[104:107]
	v_mfma_f32_16x16x32_bf16 v[92:95], v[150:153], v[204:207], v[92:95]
	v_mfma_f32_16x16x32_bf16 v[88:91], v[158:161], v[204:207], v[88:91]
	v_mfma_f32_16x16x32_bf16 v[76:79], v[150:153], v[212:215], v[76:79]
	v_mfma_f32_16x16x32_bf16 v[72:75], v[158:161], v[212:215], v[72:75]
	v_mfma_f32_16x16x32_bf16 v[116:119], v[162:165], v[184:187], v[116:119]
	v_mfma_f32_16x16x32_bf16 v[112:115], v[170:173], v[184:187], v[112:115]
	v_mfma_f32_16x16x32_bf16 v[100:103], v[162:165], v[192:195], v[100:103]
	v_mfma_f32_16x16x32_bf16 v[96:99], v[170:173], v[192:195], v[96:99]
	v_mfma_f32_16x16x32_bf16 v[84:87], v[162:165], v[200:203], v[84:87]
	v_mfma_f32_16x16x32_bf16 v[80:83], v[170:173], v[200:203], v[80:83]
	v_mfma_f32_16x16x32_bf16 v[68:71], v[162:165], v[208:211], v[68:71]
	v_mfma_f32_16x16x32_bf16 v[64:67], v[170:173], v[208:211], v[64:67]
	v_mfma_f32_16x16x32_bf16 v[116:119], v[166:169], v[188:191], v[116:119]
	v_mfma_f32_16x16x32_bf16 v[112:115], v[180:183], v[188:191], v[112:115]
	v_mfma_f32_16x16x32_bf16 v[100:103], v[166:169], v[196:199], v[100:103]
	v_mfma_f32_16x16x32_bf16 v[96:99], v[180:183], v[196:199], v[96:99]
	v_mfma_f32_16x16x32_bf16 v[84:87], v[166:169], v[204:207], v[84:87]
	v_mfma_f32_16x16x32_bf16 v[80:83], v[180:183], v[204:207], v[80:83]
	v_mfma_f32_16x16x32_bf16 v[68:71], v[166:169], v[212:215], v[68:71]
	v_mfma_f32_16x16x32_bf16 v[64:67], v[180:183], v[212:215], v[64:67]
	s_barrier
	s_add_i32 s24, s78, s2
	v_lshl_add_u64 v[174:175], v[174:175], 0, s[4:5]
	s_mov_b32 m0, s24
	ds_read_b128 v[184:187], v149 offset:49152
	ds_read_b128 v[188:191], v149 offset:50176
	ds_read_b128 v[192:195], v149 offset:51200
	ds_read_b128 v[196:199], v149 offset:52224
	ds_read_b128 v[200:203], v149 offset:53248
	ds_read_b128 v[204:207], v149 offset:54272
	ds_read_b128 v[208:211], v149 offset:55296
	ds_read_b128 v[212:215], v149 offset:56320
	global_load_lds_dwordx4 v[174:175], off
	s_add_i32 m0, s24, 0x2000
	s_add_u32 s22, s22, 0x80080
	v_lshl_add_u64 v[174:175], v[216:217], 0, s[4:5]
	s_addc_u32 s23, s23, 0
	s_add_i32 s24, s79, s2
	global_load_lds_dwordx4 v[174:175], off
	s_mov_b32 m0, s24
	s_nop 0
	global_load_lds_dwordx4 v130, s[22:23]
	s_add_i32 m0, s24, 0x2000
	s_nop 0
	global_load_lds_dwordx4 v134, s[22:23]
	v_lshl_add_u64 v[174:175], v[218:219], 0, s[4:5]
	s_mov_b32 m0, s29
	s_nop 0
	global_load_lds_dwordx4 v[174:175], off
	v_lshl_add_u64 v[174:175], v[220:221], 0, s[4:5]
	s_mov_b32 m0, s33
	s_nop 0
	global_load_lds_dwordx4 v[174:175], off
	s_waitcnt vmcnt(8) lgkmcnt(0)
	s_barrier
	v_mfma_f32_16x16x32_bf16 v[60:63], v[140:143], v[184:187], v[60:63]
	v_mfma_f32_16x16x32_bf16 v[56:59], v[154:157], v[184:187], v[56:59]
	v_mfma_f32_16x16x32_bf16 v[44:47], v[140:143], v[192:195], v[44:47]
	v_mfma_f32_16x16x32_bf16 v[40:43], v[154:157], v[192:195], v[40:43]
	v_mfma_f32_16x16x32_bf16 v[28:31], v[140:143], v[200:203], v[28:31]
	v_mfma_f32_16x16x32_bf16 v[24:27], v[154:157], v[200:203], v[24:27]
	v_mfma_f32_16x16x32_bf16 v[12:15], v[140:143], v[208:211], v[12:15]
	v_mfma_f32_16x16x32_bf16 v[8:11], v[154:157], v[208:211], v[8:11]
	v_mfma_f32_16x16x32_bf16 v[60:63], v[150:153], v[188:191], v[60:63]
	v_mfma_f32_16x16x32_bf16 v[56:59], v[158:161], v[188:191], v[56:59]
	v_mfma_f32_16x16x32_bf16 v[44:47], v[150:153], v[196:199], v[44:47]
	v_mfma_f32_16x16x32_bf16 v[40:43], v[158:161], v[196:199], v[40:43]
	v_mfma_f32_16x16x32_bf16 v[28:31], v[150:153], v[204:207], v[28:31]
	v_mfma_f32_16x16x32_bf16 v[24:27], v[158:161], v[204:207], v[24:27]
	v_mfma_f32_16x16x32_bf16 v[12:15], v[150:153], v[212:215], v[12:15]
	v_mfma_f32_16x16x32_bf16 v[8:11], v[158:161], v[212:215], v[8:11]
	v_mfma_f32_16x16x32_bf16 v[52:55], v[162:165], v[184:187], v[52:55]
	v_mfma_f32_16x16x32_bf16 v[48:51], v[170:173], v[184:187], v[48:51]
	v_mfma_f32_16x16x32_bf16 v[36:39], v[162:165], v[192:195], v[36:39]
	v_mfma_f32_16x16x32_bf16 v[32:35], v[170:173], v[192:195], v[32:35]
	v_mfma_f32_16x16x32_bf16 v[20:23], v[162:165], v[200:203], v[20:23]
	v_mfma_f32_16x16x32_bf16 v[16:19], v[170:173], v[200:203], v[16:19]
	v_mfma_f32_16x16x32_bf16 v[4:7], v[162:165], v[208:211], v[4:7]
	v_mfma_f32_16x16x32_bf16 v[0:3], v[170:173], v[208:211], v[0:3]
	v_mfma_f32_16x16x32_bf16 v[52:55], v[166:169], v[188:191], v[52:55]
	v_mfma_f32_16x16x32_bf16 v[48:51], v[180:183], v[188:191], v[48:51]
	v_mfma_f32_16x16x32_bf16 v[36:39], v[166:169], v[196:199], v[36:39]
	v_mfma_f32_16x16x32_bf16 v[32:35], v[180:183], v[196:199], v[32:35]
	v_mfma_f32_16x16x32_bf16 v[20:23], v[166:169], v[204:207], v[20:23]
	v_mfma_f32_16x16x32_bf16 v[16:19], v[180:183], v[204:207], v[16:19]
	v_mfma_f32_16x16x32_bf16 v[4:7], v[166:169], v[212:215], v[4:7]
	v_mfma_f32_16x16x32_bf16 v[0:3], v[180:183], v[212:215], v[0:3]
	s_barrier
	s_add_i32 s75, s75, 2
	s_add_u32 s20, s20, 0x100
	s_addc_u32 s21, s21, 0
	s_add_u32 s13, s13, 0x100
	s_addc_u32 s74, s74, 0
	s_cmp_gt_u32 s75, 29

; #define PG8_STAGE(bufoff, gbase, voff) do { _Pragma("unroll") for (int _i = 0; _i < 2; ++_i) \
;         __builtin_amdgcn_global_load_lds((const unsigned*)((const char*)(gbase) + (voff)[_i]), (LAS unsigned*)(lds + (bufoff) + ldsw + _i * 8192), 16, 0, 0); } while (0)
; #define PG8_LDA(dst, b, h) do { _Pragma("unroll") for (int m = 0; m < 4; ++m) _Pragma("unroll") for (int k = 0; k < 2; ++k) dst[m][k] = *(const LAS bf16x8*)(lds + PG8_SA(b, h) + aoff + m * 2048 + k * 1024); } while (0)
; #define PG8_LDB(dst, b, h) do { _Pragma("unroll") for (int n = 0; n < 2; ++n) _Pragma("unroll") for (int k = 0; k < 2; ++k) dst[n][k] = *(const LAS bf16x8*)(lds + PG8_SB(b, h) + boff + n * 2048 + k * 1024); } while (0)
; #define PG8_MMA(ai, bj, At, Bt) do { __builtin_amdgcn_s_setprio(1); _Pragma("unroll") for (int m = 0; m < 4; ++m) _Pragma("unroll") for (int n = 0; n < 2; ++n) _Pragma("unroll") for (int k = 0; k < 2; ++k) \
;         acc[ai][bj][m][n] = __builtin_amdgcn_mfma_f32_16x16x32_bf16(Bt[n][k], At[m][k], acc[ai][bj][m][n], 0, 0, 0); __builtin_amdgcn_s_setprio(0); } while (0)
; #define PG8_WAIT_V(n) asm volatile("s_waitcnt vmcnt(" #n ")" ::: "memory")
; #define PG8_WAIT_L(n) asm volatile("s_waitcnt lgkmcnt(" #n ")" ::: "memory")
; #define PG8_BAR __builtin_amdgcn_s_barrier()
; #define PG8_SCHED __builtin_amdgcn_sched_barrier(0)
; template <class Sched, class Epi, bool ALIGN_EPI, bool SP2>
; __device__ __forceinline__ void gemm_phase(LAS unsigned char* lds, const int K, const int lda, const int ldb, const Sched& S, const Epi& E) {
;     ...
;     f32x4 acc[2][2][4][2];
; #pragma unroll
;     for (int a = 0; a < 2; ++a)
; #pragma unroll
;         for (int b = 0; b < 2; ++b)
; #pragma unroll
;             for (int m = 0; m < 4; ++m)
; #pragma unroll
;                 for (int n = 0; n < 2; ++n) acc[a][b][m][n] = (f32x4){0.f, 0.f, 0.f, 0.f};
;     ...
;             PG8_LDB(B0, 0, 0); PG8_LDB(B1, 0, 1); PG8_SCHED; PG8_LDA(At, 0, 0); PG8_STAGE(PG8_SA(1, 1), a1 + hstepA, voffA);
;             PG8_WAIT_V(8); PG8_WAIT_L(0); PG8_BAR; PG8_MMA(0, 0, At, B0); PG8_MMA(0, 1, At, B1); PG8_BAR; PG8_SCHED;
;             PG8_LDA(At, 0, 1); PG8_STAGE(PG8_SB(0, 0), b2, voffB); PG8_STAGE(PG8_SB(0, 1), b2 + hstepB, voffB); PG8_STAGE(PG8_SA(0, 0), a2, voffA);
;             PG8_WAIT_V(8); PG8_WAIT_L(0); PG8_BAR; PG8_MMA(1, 0, At, B0); PG8_MMA(1, 1, At, B1); PG8_BAR; PG8_SCHED;
.LBB0_242:
	s_add_u32 s89, s22, 0x100
	v_mov_b32_e32 v0, 0
	s_addc_u32 s90, s23, 0
	s_mov_b32 s91, -2
	v_mov_b32_e32 v1, v0
	s_waitcnt lgkmcnt(0)
	v_readlane_b32 s98, v255, 13
	s_nop 4
	s_cmp_gt_u32 s98, 3
	s_cbranch_scc1 .Lprio_skip_243
	s_setprio 1
.Lprio_skip_243:
	ds_read_b128 v[124:127], v169
	ds_read_b128 v[132:135], v169 offset:1024
	ds_read_b128 v[136:139], v169 offset:2048
	ds_read_b128 v[140:143], v169 offset:3072
	ds_read_b128 v[144:147], v170
	ds_read_b128 v[156:159], v170 offset:1024
	ds_read_b128 v[160:163], v170 offset:2048
	ds_read_b128 v[182:185], v170 offset:3072
	s_add_u32 s22, s20, 0x100
	s_addc_u32 s23, s21, 0
	s_cmpk_eq_i32 s91, 0x54
	s_cselect_b32 s27, s17, s23
	s_cselect_b32 s26, s16, s22
	s_cselect_b32 s25, s19, s90
	s_cselect_b32 s24, s18, s89
	s_mov_b32 m0, s78
	ds_read_b128 v[186:189], v171
	ds_read_b128 v[190:193], v171 offset:1024
	ds_read_b128 v[194:197], v171 offset:2048
	ds_read_b128 v[198:201], v171 offset:3072
	ds_read_b128 v[202:205], v171 offset:4096
	ds_read_b128 v[206:209], v171 offset:5120
	ds_read_b128 v[210:213], v171 offset:6144
	ds_read_b128 v[214:217], v171 offset:7168
	global_load_lds_dwordx4 v152, s[20:21]
	s_mov_b32 m0, s79
	s_nop 0
	global_load_lds_dwordx4 v154, s[20:21]
	s_waitcnt vmcnt(8) lgkmcnt(0)
	s_barrier
	v_mfma_f32_16x16x32_bf16 v[128:131], v[124:127], v[186:189], 0
	v_mfma_f32_16x16x32_bf16 v[120:123], v[136:139], v[186:189], 0
	v_mfma_f32_16x16x32_bf16 v[108:111], v[124:127], v[194:197], 0
	v_mfma_f32_16x16x32_bf16 v[104:107], v[136:139], v[194:197], 0
	v_mfma_f32_16x16x32_bf16 v[92:95], v[124:127], v[202:205], 0
	v_mfma_f32_16x16x32_bf16 v[88:91], v[136:139], v[202:205], 0
	v_mfma_f32_16x16x32_bf16 v[76:79], v[124:127], v[210:213], 0
	v_mfma_f32_16x16x32_bf16 v[72:75], v[136:139], v[210:213], 0
	v_mfma_f32_16x16x32_bf16 v[128:131], v[132:135], v[190:193], v[128:131]
	v_mfma_f32_16x16x32_bf16 v[120:123], v[140:143], v[190:193], v[120:123]
	v_mfma_f32_16x16x32_bf16 v[108:111], v[132:135], v[198:201], v[108:111]
	v_mfma_f32_16x16x32_bf16 v[104:107], v[140:143], v[198:201], v[104:107]
	v_mfma_f32_16x16x32_bf16 v[92:95], v[132:135], v[206:209], v[92:95]
	v_mfma_f32_16x16x32_bf16 v[88:91], v[140:143], v[206:209], v[88:91]
	v_mfma_f32_16x16x32_bf16 v[76:79], v[132:135], v[214:217], v[76:79]
	v_mfma_f32_16x16x32_bf16 v[72:75], v[140:143], v[214:217], v[72:75]
	v_mfma_f32_16x16x32_bf16 v[116:119], v[144:147], v[186:189], 0
	v_mfma_f32_16x16x32_bf16 v[112:115], v[160:163], v[186:189], 0
	v_mfma_f32_16x16x32_bf16 v[100:103], v[144:147], v[194:197], 0
	v_mfma_f32_16x16x32_bf16 v[96:99], v[160:163], v[194:197], 0
	v_mfma_f32_16x16x32_bf16 v[84:87], v[144:147], v[202:205], 0
	v_mfma_f32_16x16x32_bf16 v[80:83], v[160:163], v[202:205], 0
	v_mfma_f32_16x16x32_bf16 v[68:71], v[144:147], v[210:213], 0
	v_mfma_f32_16x16x32_bf16 v[64:67], v[160:163], v[210:213], 0
	v_mfma_f32_16x16x32_bf16 v[116:119], v[156:159], v[190:193], v[116:119]
	v_mfma_f32_16x16x32_bf16 v[112:115], v[182:185], v[190:193], v[112:115]
	v_mfma_f32_16x16x32_bf16 v[100:103], v[156:159], v[198:201], v[100:103]
	v_mfma_f32_16x16x32_bf16 v[96:99], v[182:185], v[198:201], v[96:99]
	v_mfma_f32_16x16x32_bf16 v[84:87], v[156:159], v[206:209], v[84:87]
	v_mfma_f32_16x16x32_bf16 v[80:83], v[182:185], v[206:209], v[80:83]
	v_mfma_f32_16x16x32_bf16 v[68:71], v[156:159], v[214:217], v[68:71]
	v_mfma_f32_16x16x32_bf16 v[64:67], v[182:185], v[214:217], v[64:67]
	s_barrier
	s_mov_b32 m0, s84
	v_lshl_add_u64 v[164:165], s[24:25], 0, v[148:149]
	ds_read_b128 v[186:189], v171 offset:16384
	ds_read_b128 v[190:193], v171 offset:17408
	ds_read_b128 v[194:197], v171 offset:18432
	ds_read_b128 v[198:201], v171 offset:19456
	ds_read_b128 v[202:205], v171 offset:20480
	ds_read_b128 v[206:209], v171 offset:21504
	ds_read_b128 v[210:213], v171 offset:22528
	ds_read_b128 v[214:217], v171 offset:23552
	global_load_lds_dwordx4 v[164:165], off
	s_add_i32 m0, s84, 0x2000
	s_add_u32 s20, s24, 0x160000
	v_lshl_add_u64 v[174:175], s[24:25], 0, v[150:151]
	s_addc_u32 s21, s25, 0
	s_add_i32 s96, s53, s13
	global_load_lds_dwordx4 v[174:175], off
	s_mov_b32 m0, s96
	v_lshl_add_u64 v[220:221], s[26:27], 0, v[150:151]
	global_load_lds_dwordx4 v148, s[20:21]
	s_add_i32 m0, s96, 0x2000
	s_nop 0
	global_load_lds_dwordx4 v150, s[20:21]
	v_lshl_add_u64 v[218:219], s[26:27], 0, v[148:149]
	s_mov_b32 m0, s28
	s_nop 0
	global_load_lds_dwordx4 v[218:219], off
	s_mov_b32 m0, s29
	s_nop 0
	global_load_lds_dwordx4 v[220:221], off
	s_waitcnt vmcnt(8) lgkmcnt(0)
	s_barrier
	v_mfma_f32_16x16x32_bf16 v[60:63], v[124:127], v[186:189], 0
	v_mfma_f32_16x16x32_bf16 v[56:59], v[136:139], v[186:189], 0
	v_mfma_f32_16x16x32_bf16 v[44:47], v[124:127], v[194:197], 0
	v_mfma_f32_16x16x32_bf16 v[40:43], v[136:139], v[194:197], 0
	v_mfma_f32_16x16x32_bf16 v[28:31], v[124:127], v[202:205], 0
	v_mfma_f32_16x16x32_bf16 v[24:27], v[136:139], v[202:205], 0
	v_mfma_f32_16x16x32_bf16 v[12:15], v[124:127], v[210:213], 0
	v_mfma_f32_16x16x32_bf16 v[8:11], v[136:139], v[210:213], 0
	v_mfma_f32_16x16x32_bf16 v[60:63], v[132:135], v[190:193], v[60:63]
	v_mfma_f32_16x16x32_bf16 v[56:59], v[140:143], v[190:193], v[56:59]
	v_mfma_f32_16x16x32_bf16 v[44:47], v[132:135], v[198:201], v[44:47]
	v_mfma_f32_16x16x32_bf16 v[40:43], v[140:143], v[198:201], v[40:43]
	v_mfma_f32_16x16x32_bf16 v[28:31], v[132:135], v[206:209], v[28:31]
	v_mfma_f32_16x16x32_bf16 v[24:27], v[140:143], v[206:209], v[24:27]
	v_mfma_f32_16x16x32_bf16 v[12:15], v[132:135], v[214:217], v[12:15]
	v_mfma_f32_16x16x32_bf16 v[8:11], v[140:143], v[214:217], v[8:11]
	v_mfma_f32_16x16x32_bf16 v[52:55], v[144:147], v[186:189], 0
	v_mfma_f32_16x16x32_bf16 v[48:51], v[160:163], v[186:189], 0
	v_mfma_f32_16x16x32_bf16 v[36:39], v[144:147], v[194:197], 0
	v_mfma_f32_16x16x32_bf16 v[32:35], v[160:163], v[194:197], 0
	v_mfma_f32_16x16x32_bf16 v[20:23], v[144:147], v[202:205], 0
	v_mfma_f32_16x16x32_bf16 v[16:19], v[160:163], v[202:205], 0
	v_mfma_f32_16x16x32_bf16 v[4:7], v[144:147], v[210:213], 0
	v_mfma_f32_16x16x32_bf16 v[0:3], v[160:163], v[210:213], 0
	v_mfma_f32_16x16x32_bf16 v[52:55], v[156:159], v[190:193], v[52:55]
	v_mfma_f32_16x16x32_bf16 v[48:51], v[182:185], v[190:193], v[48:51]
	v_mfma_f32_16x16x32_bf16 v[36:39], v[156:159], v[198:201], v[36:39]
	v_mfma_f32_16x16x32_bf16 v[32:35], v[182:185], v[198:201], v[32:35]
	v_mfma_f32_16x16x32_bf16 v[20:23], v[156:159], v[206:209], v[20:23]
	v_mfma_f32_16x16x32_bf16 v[16:19], v[182:185], v[206:209], v[16:19]
	v_mfma_f32_16x16x32_bf16 v[4:7], v[156:159], v[214:217], v[4:7]
	v_mfma_f32_16x16x32_bf16 v[0:3], v[182:185], v[214:217], v[0:3]
	s_barrier
; #define PG8_STAGE(bufoff, gbase, voff) do { _Pragma("unroll") for (int _i = 0; _i < 2; ++_i) \
;         __builtin_amdgcn_global_load_lds((const unsigned*)((const char*)(gbase) + (voff)[_i]), (LAS unsigned*)(lds + (bufoff) + ldsw + _i * 8192), 16, 0, 0); } while (0)
; #define PG8_LDA(dst, b, h) do { _Pragma("unroll") for (int m = 0; m < 4; ++m) _Pragma("unroll") for (int k = 0; k < 2; ++k) dst[m][k] = *(const LAS bf16x8*)(lds + PG8_SA(b, h) + aoff + m * 2048 + k * 1024); } while (0)
; #define PG8_LDB(dst, b, h) do { _Pragma("unroll") for (int n = 0; n < 2; ++n) _Pragma("unroll") for (int k = 0; k < 2; ++k) dst[n][k] = *(const LAS bf16x8*)(lds + PG8_SB(b, h) + boff + n * 2048 + k * 1024); } while (0)
; #define PG8_MMA(ai, bj, At, Bt) do { __builtin_amdgcn_s_setprio(1); _Pragma("unroll") for (int m = 0; m < 4; ++m) _Pragma("unroll") for (int n = 0; n < 2; ++n) _Pragma("unroll") for (int k = 0; k < 2; ++k) \
;         acc[ai][bj][m][n] = __builtin_amdgcn_mfma_f32_16x16x32_bf16(Bt[n][k], At[m][k], acc[ai][bj][m][n], 0, 0, 0); __builtin_amdgcn_s_setprio(0); } while (0)
; #define PG8_WAIT_V(n) asm volatile("s_waitcnt vmcnt(" #n ")" ::: "memory")
; #define PG8_WAIT_L(n) asm volatile("s_waitcnt lgkmcnt(" #n ")" ::: "memory")
; #define PG8_BAR __builtin_amdgcn_s_barrier()
; #define PG8_SCHED __builtin_amdgcn_sched_barrier(0)
; template <class Sched, class Epi, bool ALIGN_EPI, bool SP2>
; __device__ __forceinline__ void gemm_phase(LAS unsigned char* lds, const int K, const int lda, const int ldb, const Sched& S, const Epi& E) {
;     ...
;             PG8_LDB(B0, 1, 0); PG8_LDB(B1, 1, 1); PG8_SCHED; PG8_LDA(At, 1, 0); PG8_STAGE(PG8_SA(0, 1), a2 + hstepA, voffA);
;             PG8_WAIT_V(8); PG8_WAIT_L(0); PG8_BAR; PG8_MMA(0, 0, At, B0); PG8_MMA(0, 1, At, B1); PG8_BAR; PG8_SCHED;
;             PG8_LDA(At, 1, 1); PG8_STAGE(PG8_SB(1, 0), b3, voffB); PG8_STAGE(PG8_SB(1, 1), b3 + hstepB, voffB); PG8_STAGE(PG8_SA(1, 0), a3, voffA);
;             PG8_WAIT_V(8); PG8_WAIT_L(0); PG8_BAR; PG8_MMA(1, 0, At, B0); PG8_MMA(1, 1, At, B1); PG8_BAR; PG8_SCHED;
	s_add_i32 s96, 0, 0x18000
	s_add_i32 s97, 0, 0x1c000
	v_add_u32_e32 v140, s96, v167
	v_add_u32_e32 v173, s97, v167
	ds_read_b128 v[124:127], v140
	ds_read_b128 v[132:135], v140 offset:1024
	ds_read_b128 v[136:139], v140 offset:2048
	ds_read_b128 v[140:143], v140 offset:3072
	ds_read_b128 v[144:147], v173
	ds_read_b128 v[156:159], v173 offset:1024
	ds_read_b128 v[160:163], v173 offset:2048
	ds_read_b128 v[182:185], v173 offset:3072
	s_add_u32 s20, s26, 0x160000
	s_addc_u32 s21, s27, 0
	s_mov_b32 m0, s33
	ds_read_b128 v[186:189], v171 offset:32768
	ds_read_b128 v[190:193], v171 offset:33792
	ds_read_b128 v[194:197], v171 offset:34816
	ds_read_b128 v[198:201], v171 offset:35840
	ds_read_b128 v[202:205], v171 offset:36864
	ds_read_b128 v[206:209], v171 offset:37888
	ds_read_b128 v[210:213], v171 offset:38912
	ds_read_b128 v[214:217], v171 offset:39936
	global_load_lds_dwordx4 v148, s[20:21]
	s_mov_b32 m0, s35
	s_nop 0
	global_load_lds_dwordx4 v150, s[20:21]
	s_waitcnt vmcnt(8) lgkmcnt(0)
	s_barrier
	v_mfma_f32_16x16x32_bf16 v[128:131], v[124:127], v[186:189], v[128:131]
	v_mfma_f32_16x16x32_bf16 v[120:123], v[136:139], v[186:189], v[120:123]
	v_mfma_f32_16x16x32_bf16 v[108:111], v[124:127], v[194:197], v[108:111]
	v_mfma_f32_16x16x32_bf16 v[104:107], v[136:139], v[194:197], v[104:107]
	v_mfma_f32_16x16x32_bf16 v[92:95], v[124:127], v[202:205], v[92:95]
	v_mfma_f32_16x16x32_bf16 v[88:91], v[136:139], v[202:205], v[88:91]
	v_mfma_f32_16x16x32_bf16 v[76:79], v[124:127], v[210:213], v[76:79]
	v_mfma_f32_16x16x32_bf16 v[72:75], v[136:139], v[210:213], v[72:75]
	v_mfma_f32_16x16x32_bf16 v[128:131], v[132:135], v[190:193], v[128:131]
	v_mfma_f32_16x16x32_bf16 v[120:123], v[140:143], v[190:193], v[120:123]
	v_mfma_f32_16x16x32_bf16 v[108:111], v[132:135], v[198:201], v[108:111]
	v_mfma_f32_16x16x32_bf16 v[104:107], v[140:143], v[198:201], v[104:107]
	v_mfma_f32_16x16x32_bf16 v[92:95], v[132:135], v[206:209], v[92:95]
	v_mfma_f32_16x16x32_bf16 v[88:91], v[140:143], v[206:209], v[88:91]
	v_mfma_f32_16x16x32_bf16 v[76:79], v[132:135], v[214:217], v[76:79]
	v_mfma_f32_16x16x32_bf16 v[72:75], v[140:143], v[214:217], v[72:75]
	v_mfma_f32_16x16x32_bf16 v[116:119], v[144:147], v[186:189], v[116:119]
	v_mfma_f32_16x16x32_bf16 v[112:115], v[160:163], v[186:189], v[112:115]
	v_mfma_f32_16x16x32_bf16 v[100:103], v[144:147], v[194:197], v[100:103]
	v_mfma_f32_16x16x32_bf16 v[96:99], v[160:163], v[194:197], v[96:99]
	v_mfma_f32_16x16x32_bf16 v[84:87], v[144:147], v[202:205], v[84:87]
	v_mfma_f32_16x16x32_bf16 v[80:83], v[160:163], v[202:205], v[80:83]
	v_mfma_f32_16x16x32_bf16 v[68:71], v[144:147], v[210:213], v[68:71]
	v_mfma_f32_16x16x32_bf16 v[64:67], v[160:163], v[210:213], v[64:67]
	v_mfma_f32_16x16x32_bf16 v[116:119], v[156:159], v[190:193], v[116:119]
	v_mfma_f32_16x16x32_bf16 v[112:115], v[182:185], v[190:193], v[112:115]
	v_mfma_f32_16x16x32_bf16 v[100:103], v[156:159], v[198:201], v[100:103]
	v_mfma_f32_16x16x32_bf16 v[96:99], v[182:185], v[198:201], v[96:99]
	v_mfma_f32_16x16x32_bf16 v[84:87], v[156:159], v[206:209], v[84:87]
	v_mfma_f32_16x16x32_bf16 v[80:83], v[182:185], v[206:209], v[80:83]
	v_mfma_f32_16x16x32_bf16 v[68:71], v[156:159], v[214:217], v[68:71]
	v_mfma_f32_16x16x32_bf16 v[64:67], v[182:185], v[214:217], v[64:67]
	s_barrier
	s_add_i32 s20, s96, s13
	v_lshl_add_u64 v[164:165], v[164:165], 0, s[6:7]
	s_mov_b32 m0, s20
	ds_read_b128 v[186:189], v171 offset:49152
	ds_read_b128 v[190:193], v171 offset:50176
	ds_read_b128 v[194:197], v171 offset:51200
	ds_read_b128 v[198:201], v171 offset:52224
	ds_read_b128 v[202:205], v171 offset:53248
	ds_read_b128 v[206:209], v171 offset:54272
	ds_read_b128 v[210:213], v171 offset:55296
	ds_read_b128 v[214:217], v171 offset:56320
	global_load_lds_dwordx4 v[164:165], off
	s_add_i32 m0, s20, 0x2000
	s_add_u32 s20, s24, 0x160080
	v_lshl_add_u64 v[164:165], v[174:175], 0, s[6:7]
	s_addc_u32 s21, s25, 0
	s_add_i32 s24, s97, s13
	global_load_lds_dwordx4 v[164:165], off
	s_mov_b32 m0, s24
	s_nop 0
	global_load_lds_dwordx4 v148, s[20:21]
	s_add_i32 m0, s24, 0x2000
	s_nop 0
	global_load_lds_dwordx4 v150, s[20:21]
	v_lshl_add_u64 v[164:165], v[218:219], 0, s[6:7]
	s_mov_b32 m0, s51
	s_nop 0
	global_load_lds_dwordx4 v[164:165], off
	v_lshl_add_u64 v[164:165], v[220:221], 0, s[6:7]
	s_mov_b32 m0, s52
	s_nop 0
	global_load_lds_dwordx4 v[164:165], off
	s_waitcnt vmcnt(8) lgkmcnt(0)
	s_barrier
	v_mfma_f32_16x16x32_bf16 v[60:63], v[124:127], v[186:189], v[60:63]
	v_mfma_f32_16x16x32_bf16 v[56:59], v[136:139], v[186:189], v[56:59]
	v_mfma_f32_16x16x32_bf16 v[44:47], v[124:127], v[194:197], v[44:47]
	v_mfma_f32_16x16x32_bf16 v[40:43], v[136:139], v[194:197], v[40:43]
	v_mfma_f32_16x16x32_bf16 v[28:31], v[124:127], v[202:205], v[28:31]
	v_mfma_f32_16x16x32_bf16 v[24:27], v[136:139], v[202:205], v[24:27]
	v_mfma_f32_16x16x32_bf16 v[12:15], v[124:127], v[210:213], v[12:15]
	v_mfma_f32_16x16x32_bf16 v[8:11], v[136:139], v[210:213], v[8:11]
	v_mfma_f32_16x16x32_bf16 v[60:63], v[132:135], v[190:193], v[60:63]
	v_mfma_f32_16x16x32_bf16 v[56:59], v[140:143], v[190:193], v[56:59]
	v_mfma_f32_16x16x32_bf16 v[44:47], v[132:135], v[198:201], v[44:47]
	v_mfma_f32_16x16x32_bf16 v[40:43], v[140:143], v[198:201], v[40:43]
	v_mfma_f32_16x16x32_bf16 v[28:31], v[132:135], v[206:209], v[28:31]
	v_mfma_f32_16x16x32_bf16 v[24:27], v[140:143], v[206:209], v[24:27]
	v_mfma_f32_16x16x32_bf16 v[12:15], v[132:135], v[214:217], v[12:15]
	v_mfma_f32_16x16x32_bf16 v[8:11], v[140:143], v[214:217], v[8:11]
	v_mfma_f32_16x16x32_bf16 v[52:55], v[144:147], v[186:189], v[52:55]
	v_mfma_f32_16x16x32_bf16 v[48:51], v[160:163], v[186:189], v[48:51]
	v_mfma_f32_16x16x32_bf16 v[36:39], v[144:147], v[194:197], v[36:39]
	v_mfma_f32_16x16x32_bf16 v[32:35], v[160:163], v[194:197], v[32:35]
	v_mfma_f32_16x16x32_bf16 v[20:23], v[144:147], v[202:205], v[20:23]
	v_mfma_f32_16x16x32_bf16 v[16:19], v[160:163], v[202:205], v[16:19]
	v_mfma_f32_16x16x32_bf16 v[4:7], v[144:147], v[210:213], v[4:7]
	v_mfma_f32_16x16x32_bf16 v[0:3], v[160:163], v[210:213], v[0:3]
	v_mfma_f32_16x16x32_bf16 v[52:55], v[156:159], v[190:193], v[52:55]
	v_mfma_f32_16x16x32_bf16 v[48:51], v[182:185], v[190:193], v[48:51]
	v_mfma_f32_16x16x32_bf16 v[36:39], v[156:159], v[198:201], v[36:39]
	v_mfma_f32_16x16x32_bf16 v[32:35], v[182:185], v[198:201], v[32:35]
	v_mfma_f32_16x16x32_bf16 v[20:23], v[156:159], v[206:209], v[20:23]
	v_mfma_f32_16x16x32_bf16 v[16:19], v[182:185], v[206:209], v[16:19]
	v_mfma_f32_16x16x32_bf16 v[4:7], v[156:159], v[214:217], v[4:7]
	v_mfma_f32_16x16x32_bf16 v[0:3], v[182:185], v[214:217], v[0:3]
	s_barrier
	s_add_i32 s91, s91, 2
	s_add_u32 s89, s89, 0x100
	s_addc_u32 s90, s90, 0
	s_cmpk_gt_u32 s91, 0x55
	s_mov_b64 s[20:21], s[22:23]

; #define PG8_STAGE(bufoff, gbase, voff) do { _Pragma("unroll") for (int _i = 0; _i < 2; ++_i) \
;         __builtin_amdgcn_global_load_lds((const unsigned*)((const char*)(gbase) + (voff)[_i]), (LAS unsigned*)(lds + (bufoff) + ldsw + _i * 8192), 16, 0, 0); } while (0)
; #define PG8_LDA(dst, b, h) do { _Pragma("unroll") for (int m = 0; m < 4; ++m) _Pragma("unroll") for (int k = 0; k < 2; ++k) dst[m][k] = *(const LAS bf16x8*)(lds + PG8_SA(b, h) + aoff + m * 2048 + k * 1024); } while (0)
; #define PG8_LDB(dst, b, h) do { _Pragma("unroll") for (int n = 0; n < 2; ++n) _Pragma("unroll") for (int k = 0; k < 2; ++k) dst[n][k] = *(const LAS bf16x8*)(lds + PG8_SB(b, h) + boff + n * 2048 + k * 1024); } while (0)
; #define PG8_MMA(ai, bj, At, Bt) do { __builtin_amdgcn_s_setprio(1); _Pragma("unroll") for (int m = 0; m < 4; ++m) _Pragma("unroll") for (int n = 0; n < 2; ++n) _Pragma("unroll") for (int k = 0; k < 2; ++k) \
;         acc[ai][bj][m][n] = __builtin_amdgcn_mfma_f32_16x16x32_bf16(Bt[n][k], At[m][k], acc[ai][bj][m][n], 0, 0, 0); __builtin_amdgcn_s_setprio(0); } while (0)
; #define PG8_WAIT_V(n) asm volatile("s_waitcnt vmcnt(" #n ")" ::: "memory")
; #define PG8_WAIT_L(n) asm volatile("s_waitcnt lgkmcnt(" #n ")" ::: "memory")
; #define PG8_BAR __builtin_amdgcn_s_barrier()
; #define PG8_SCHED __builtin_amdgcn_sched_barrier(0)
; template <class Sched, class Epi, bool ALIGN_EPI, bool SP2>
; __device__ __forceinline__ void gemm_phase(LAS unsigned char* lds, const int K, const int lda, const int ldb, const Sched& S, const Epi& E) {
;     ...
;     f32x4 acc[2][2][4][2];
; #pragma unroll
;     for (int a = 0; a < 2; ++a)
; #pragma unroll
;         for (int b = 0; b < 2; ++b)
; #pragma unroll
;             for (int m = 0; m < 4; ++m)
; #pragma unroll
;                 for (int n = 0; n < 2; ++n) acc[a][b][m][n] = (f32x4){0.f, 0.f, 0.f, 0.f};
;     ...
;             PG8_LDB(B0, 0, 0); PG8_LDB(B1, 0, 1); PG8_SCHED; PG8_LDA(At, 0, 0); PG8_STAGE(PG8_SA(1, 1), a1 + hstepA, voffA);
;             PG8_WAIT_V(8); PG8_WAIT_L(0); PG8_BAR; PG8_MMA(0, 0, At, B0); PG8_MMA(0, 1, At, B1); PG8_BAR; PG8_SCHED;
;             PG8_LDA(At, 0, 1); PG8_STAGE(PG8_SB(0, 0), b2, voffB); PG8_STAGE(PG8_SB(0, 1), b2 + hstepB, voffB); PG8_STAGE(PG8_SA(0, 0), a2, voffA);
;             PG8_WAIT_V(8); PG8_WAIT_L(0); PG8_BAR; PG8_MMA(1, 0, At, B0); PG8_MMA(1, 1, At, B1); PG8_BAR; PG8_SCHED;
.LBB0_352:
	s_and_b64 s[6:7], s[24:25], exec
	s_cselect_b32 s1, s19, s27
	s_cselect_b32 s4, s18, s26
	s_cselect_b32 s21, s23, s29
	s_cselect_b32 vcc_lo, s22, s28
	s_add_u32 s26, s26, 0x80080
	s_addc_u32 s27, s27, 0
	s_add_u32 vcc_hi, s28, 0x100
	v_mov_b32_e32 v0, 0
	s_addc_u32 s6, s29, 0
	s_mov_b32 s7, -2
	v_readlane_b32 s98, v255, 13
	s_nop 4
	s_cmp_gt_u32 s98, 3
	s_cbranch_scc1 .Lprio_skip_353
	s_setprio 1
.Lprio_skip_353:
	s_waitcnt lgkmcnt(0)
	ds_read_b128 v[32:35], v211
	ds_read_b128 v[36:39], v211 offset:1024
	ds_read_b128 v[48:51], v211 offset:2048
	ds_read_b128 v[52:55], v211 offset:3072
	ds_read_b128 v[56:59], v212
	ds_read_b128 v[60:63], v212 offset:1024
	ds_read_b128 v[64:67], v212 offset:2048
	ds_read_b128 v[68:71], v212 offset:3072
	s_add_u32 s8, s26, 0xfff80080
	s_addc_u32 s9, s27, -1
	s_cmp_eq_u32 s7, 28
	s_cselect_b32 s37, s1, s9
	s_cselect_b32 s36, s4, s8
	s_cselect_b32 s29, s21, s6
	s_cselect_b32 s28, vcc_lo, vcc_hi
	s_add_i32 m0, s89, 0xc000
	ds_read_b128 v[76:79], v213
	ds_read_b128 v[80:83], v213 offset:1024
	ds_read_b128 v[88:91], v213 offset:2048
	ds_read_b128 v[92:95], v213 offset:3072
	ds_read_b128 v[196:199], v213 offset:4096
	ds_read_b128 v[200:203], v213 offset:5120
	ds_read_b128 v[204:207], v213 offset:6144
	ds_read_b128 v[216:219], v213 offset:7168
	global_load_lds_dwordx4 v192, s[26:27]
	s_add_i32 m0, s89, 0xe000
	s_nop 0
	global_load_lds_dwordx4 v194, s[26:27]
	s_waitcnt vmcnt(8) lgkmcnt(0)
	s_barrier
	v_mfma_f32_16x16x32_bf16 v[172:175], v[32:35], v[76:79], 0
	v_mfma_f32_16x16x32_bf16 v[168:171], v[48:51], v[76:79], 0
	v_mfma_f32_16x16x32_bf16 v[156:159], v[32:35], v[88:91], 0
	v_mfma_f32_16x16x32_bf16 v[152:155], v[48:51], v[88:91], 0
	v_mfma_f32_16x16x32_bf16 v[140:143], v[32:35], v[196:199], 0
	v_mfma_f32_16x16x32_bf16 v[136:139], v[48:51], v[196:199], 0
	v_mfma_f32_16x16x32_bf16 v[124:127], v[32:35], v[204:207], 0
	v_mfma_f32_16x16x32_bf16 v[120:123], v[48:51], v[204:207], 0
	v_mfma_f32_16x16x32_bf16 v[172:175], v[36:39], v[80:83], v[172:175]
	v_mfma_f32_16x16x32_bf16 v[168:171], v[52:55], v[80:83], v[168:171]
	v_mfma_f32_16x16x32_bf16 v[156:159], v[36:39], v[92:95], v[156:159]
	v_mfma_f32_16x16x32_bf16 v[152:155], v[52:55], v[92:95], v[152:155]
	v_mfma_f32_16x16x32_bf16 v[140:143], v[36:39], v[200:203], v[140:143]
	v_mfma_f32_16x16x32_bf16 v[136:139], v[52:55], v[200:203], v[136:139]
	v_mfma_f32_16x16x32_bf16 v[124:127], v[36:39], v[216:219], v[124:127]
	v_mfma_f32_16x16x32_bf16 v[120:123], v[52:55], v[216:219], v[120:123]
	v_mfma_f32_16x16x32_bf16 v[164:167], v[56:59], v[76:79], 0
	v_mfma_f32_16x16x32_bf16 v[76:79], v[64:67], v[76:79], 0
	v_mfma_f32_16x16x32_bf16 v[164:167], v[60:63], v[80:83], v[164:167]
	v_mfma_f32_16x16x32_bf16 v[76:79], v[68:71], v[80:83], v[76:79]
	v_mfma_f32_16x16x32_bf16 v[80:83], v[56:59], v[88:91], 0
	v_mfma_f32_16x16x32_bf16 v[88:91], v[64:67], v[88:91], 0
	v_mfma_f32_16x16x32_bf16 v[128:131], v[64:67], v[196:199], 0
	v_mfma_f32_16x16x32_bf16 v[116:119], v[56:59], v[204:207], 0
	v_mfma_f32_16x16x32_bf16 v[112:115], v[64:67], v[204:207], 0
	v_mfma_f32_16x16x32_bf16 v[80:83], v[60:63], v[92:95], v[80:83]
	v_mfma_f32_16x16x32_bf16 v[88:91], v[68:71], v[92:95], v[88:91]
	v_mfma_f32_16x16x32_bf16 v[92:95], v[56:59], v[196:199], 0
	v_mfma_f32_16x16x32_bf16 v[128:131], v[68:71], v[200:203], v[128:131]
	v_mfma_f32_16x16x32_bf16 v[116:119], v[60:63], v[216:219], v[116:119]
	v_mfma_f32_16x16x32_bf16 v[112:115], v[68:71], v[216:219], v[112:115]
	v_mfma_f32_16x16x32_bf16 v[92:95], v[60:63], v[200:203], v[92:95]
	s_barrier
	s_add_i32 s8, s85, s88
	v_lshl_add_u64 v[208:209], s[28:29], 0, v[186:187]
	s_mov_b32 m0, s8
	ds_read_b128 v[132:135], v213 offset:16384
	ds_read_b128 v[144:147], v213 offset:17408
	ds_read_b128 v[148:151], v213 offset:18432
	ds_read_b128 v[160:163], v213 offset:19456
	ds_read_b128 v[196:199], v213 offset:20480
	ds_read_b128 v[200:203], v213 offset:21504
	ds_read_b128 v[204:207], v213 offset:22528
	ds_read_b128 v[216:219], v213 offset:23552
	global_load_lds_dwordx4 v[208:209], off
	s_add_i32 m0, s8, 0x2000
	s_add_u32 s8, s28, 0x80000
	v_lshl_add_u64 v[228:229], s[28:29], 0, v[190:191]
	s_addc_u32 s9, s29, 0
	s_add_i32 s51, s50, s88
	global_load_lds_dwordx4 v[228:229], off
	s_mov_b32 m0, s51
	v_lshl_add_u64 v[230:231], s[36:37], 0, v[184:185]
	global_load_lds_dwordx4 v186, s[8:9]
	s_add_i32 m0, s51, 0x2000
	v_lshl_add_u64 v[232:233], s[36:37], 0, v[188:189]
	global_load_lds_dwordx4 v190, s[8:9]
	s_mov_b32 m0, s89
	s_nop 0
	global_load_lds_dwordx4 v[230:231], off
	s_mov_b32 m0, s90
	s_nop 0
	global_load_lds_dwordx4 v[232:233], off
	s_waitcnt vmcnt(8) lgkmcnt(0)
	s_barrier
; #define PG8_STAGE(bufoff, gbase, voff) do { _Pragma("unroll") for (int _i = 0; _i < 2; ++_i) \
;         __builtin_amdgcn_global_load_lds((const unsigned*)((const char*)(gbase) + (voff)[_i]), (LAS unsigned*)(lds + (bufoff) + ldsw + _i * 8192), 16, 0, 0); } while (0)
; #define PG8_LDA(dst, b, h) do { _Pragma("unroll") for (int m = 0; m < 4; ++m) _Pragma("unroll") for (int k = 0; k < 2; ++k) dst[m][k] = *(const LAS bf16x8*)(lds + PG8_SA(b, h) + aoff + m * 2048 + k * 1024); } while (0)
; #define PG8_LDB(dst, b, h) do { _Pragma("unroll") for (int n = 0; n < 2; ++n) _Pragma("unroll") for (int k = 0; k < 2; ++k) dst[n][k] = *(const LAS bf16x8*)(lds + PG8_SB(b, h) + boff + n * 2048 + k * 1024); } while (0)
; #define PG8_MMA(ai, bj, At, Bt) do { __builtin_amdgcn_s_setprio(1); _Pragma("unroll") for (int m = 0; m < 4; ++m) _Pragma("unroll") for (int n = 0; n < 2; ++n) _Pragma("unroll") for (int k = 0; k < 2; ++k) \
;         acc[ai][bj][m][n] = __builtin_amdgcn_mfma_f32_16x16x32_bf16(Bt[n][k], At[m][k], acc[ai][bj][m][n], 0, 0, 0); __builtin_amdgcn_s_setprio(0); } while (0)
; #define PG8_WAIT_V(n) asm volatile("s_waitcnt vmcnt(" #n ")" ::: "memory")
; #define PG8_WAIT_L(n) asm volatile("s_waitcnt lgkmcnt(" #n ")" ::: "memory")
; #define PG8_BAR __builtin_amdgcn_s_barrier()
; #define PG8_SCHED __builtin_amdgcn_sched_barrier(0)
; template <class Sched, class Epi, bool ALIGN_EPI, bool SP2>
; __device__ __forceinline__ void gemm_phase(LAS unsigned char* lds, const int K, const int lda, const int ldb, const Sched& S, const Epi& E) {
;     ...
;             PG8_WAIT_V(8); PG8_WAIT_L(0); PG8_BAR; PG8_MMA(1, 0, At, B0); PG8_MMA(1, 1, At, B1); PG8_BAR; PG8_SCHED;
;             PG8_LDB(B0, 1, 0); PG8_LDB(B1, 1, 1); PG8_SCHED; PG8_LDA(At, 1, 0); PG8_STAGE(PG8_SA(0, 1), a2 + hstepA, voffA);
;             PG8_WAIT_V(8); PG8_WAIT_L(0); PG8_BAR; PG8_MMA(0, 0, At, B0); PG8_MMA(0, 1, At, B1); PG8_BAR; PG8_SCHED;
	v_mfma_f32_16x16x32_bf16 v[108:111], v[32:35], v[132:135], 0
	v_mfma_f32_16x16x32_bf16 v[104:107], v[48:51], v[132:135], 0
	v_mfma_f32_16x16x32_bf16 v[84:87], v[32:35], v[148:151], 0
	v_mfma_f32_16x16x32_bf16 v[72:75], v[48:51], v[148:151], 0
	v_mfma_f32_16x16x32_bf16 v[28:31], v[32:35], v[196:199], 0
	v_mfma_f32_16x16x32_bf16 v[24:27], v[48:51], v[196:199], 0
	v_mfma_f32_16x16x32_bf16 v[12:15], v[32:35], v[204:207], 0
	v_mfma_f32_16x16x32_bf16 v[8:11], v[48:51], v[204:207], 0
	v_mfma_f32_16x16x32_bf16 v[108:111], v[36:39], v[144:147], v[108:111]
	v_mfma_f32_16x16x32_bf16 v[104:107], v[52:55], v[144:147], v[104:107]
	v_mfma_f32_16x16x32_bf16 v[84:87], v[36:39], v[160:163], v[84:87]
	v_mfma_f32_16x16x32_bf16 v[72:75], v[52:55], v[160:163], v[72:75]
	v_mfma_f32_16x16x32_bf16 v[28:31], v[36:39], v[200:203], v[28:31]
	v_mfma_f32_16x16x32_bf16 v[24:27], v[52:55], v[200:203], v[24:27]
	v_mfma_f32_16x16x32_bf16 v[12:15], v[36:39], v[216:219], v[12:15]
	v_mfma_f32_16x16x32_bf16 v[8:11], v[52:55], v[216:219], v[8:11]
	v_mfma_f32_16x16x32_bf16 v[44:47], v[56:59], v[148:151], 0
	v_mfma_f32_16x16x32_bf16 v[40:43], v[64:67], v[148:151], 0
	v_mfma_f32_16x16x32_bf16 v[20:23], v[56:59], v[196:199], 0
	v_mfma_f32_16x16x32_bf16 v[16:19], v[64:67], v[196:199], 0
	v_mfma_f32_16x16x32_bf16 v[4:7], v[56:59], v[204:207], 0
	v_mfma_f32_16x16x32_bf16 v[0:3], v[64:67], v[204:207], 0
	v_mfma_f32_16x16x32_bf16 v[32:35], v[56:59], v[132:135], 0
	v_mfma_f32_16x16x32_bf16 v[36:39], v[64:67], v[132:135], 0
	v_mfma_f32_16x16x32_bf16 v[44:47], v[60:63], v[160:163], v[44:47]
	v_mfma_f32_16x16x32_bf16 v[40:43], v[68:71], v[160:163], v[40:43]
	v_mfma_f32_16x16x32_bf16 v[20:23], v[60:63], v[200:203], v[20:23]
	v_mfma_f32_16x16x32_bf16 v[16:19], v[68:71], v[200:203], v[16:19]
	v_mfma_f32_16x16x32_bf16 v[4:7], v[60:63], v[216:219], v[4:7]
	v_mfma_f32_16x16x32_bf16 v[0:3], v[68:71], v[216:219], v[0:3]
	v_mfma_f32_16x16x32_bf16 v[32:35], v[60:63], v[144:147], v[32:35]
	v_mfma_f32_16x16x32_bf16 v[36:39], v[68:71], v[144:147], v[36:39]
	s_barrier
	s_add_i32 s51, 0, 0x18000
	s_add_i32 s17, 0, 0x1c000
	v_add_u32_e32 v60, s51, v183
	v_add_u32_e32 v96, s17, v183
	ds_read_b128 v[48:51], v60
	ds_read_b128 v[52:55], v60 offset:1024
	ds_read_b128 v[56:59], v60 offset:2048
	ds_read_b128 v[60:63], v60 offset:3072
	ds_read_b128 v[64:67], v96
	ds_read_b128 v[68:71], v96 offset:1024
	ds_read_b128 v[196:199], v96 offset:2048
	ds_read_b128 v[200:203], v96 offset:3072
	s_add_u32 s8, s36, 0x80000
	s_addc_u32 s9, s37, 0
	s_mov_b32 m0, s91
	ds_read_b128 v[96:99], v213 offset:32768
	ds_read_b128 v[100:103], v213 offset:33792
	ds_read_b128 v[132:135], v213 offset:34816
	ds_read_b128 v[144:147], v213 offset:35840
	ds_read_b128 v[204:207], v213 offset:36864
	ds_read_b128 v[216:219], v213 offset:37888
	ds_read_b128 v[220:223], v213 offset:38912
	ds_read_b128 v[224:227], v213 offset:39936
	global_load_lds_dwordx4 v184, s[8:9]
	s_mov_b32 m0, s96
	s_nop 0
	global_load_lds_dwordx4 v188, s[8:9]
	s_waitcnt vmcnt(8) lgkmcnt(0)
	s_barrier
	v_mfma_f32_16x16x32_bf16 v[148:151], v[48:51], v[96:99], v[172:175]
	v_mfma_f32_16x16x32_bf16 v[172:175], v[52:55], v[100:103], v[148:151]
	v_mfma_f32_16x16x32_bf16 v[148:151], v[56:59], v[96:99], v[168:171]
	v_mfma_f32_16x16x32_bf16 v[168:171], v[60:63], v[100:103], v[148:151]
	v_mfma_f32_16x16x32_bf16 v[148:151], v[48:51], v[132:135], v[156:159]
	v_mfma_f32_16x16x32_bf16 v[156:159], v[52:55], v[144:147], v[148:151]
	v_mfma_f32_16x16x32_bf16 v[148:151], v[56:59], v[132:135], v[152:155]
	v_mfma_f32_16x16x32_bf16 v[140:143], v[48:51], v[204:207], v[140:143]
	v_mfma_f32_16x16x32_bf16 v[136:139], v[56:59], v[204:207], v[136:139]
	v_mfma_f32_16x16x32_bf16 v[124:127], v[48:51], v[220:223], v[124:127]
	v_mfma_f32_16x16x32_bf16 v[120:123], v[56:59], v[220:223], v[120:123]
	v_mfma_f32_16x16x32_bf16 v[152:155], v[60:63], v[144:147], v[148:151]
	v_mfma_f32_16x16x32_bf16 v[140:143], v[52:55], v[216:219], v[140:143]
	v_mfma_f32_16x16x32_bf16 v[136:139], v[60:63], v[216:219], v[136:139]
	v_mfma_f32_16x16x32_bf16 v[124:127], v[52:55], v[224:227], v[124:127]
	v_mfma_f32_16x16x32_bf16 v[120:123], v[60:63], v[224:227], v[120:123]
	v_mfma_f32_16x16x32_bf16 v[76:79], v[196:199], v[96:99], v[76:79]
	v_mfma_f32_16x16x32_bf16 v[148:151], v[64:67], v[96:99], v[164:167]
	v_mfma_f32_16x16x32_bf16 v[160:163], v[200:203], v[100:103], v[76:79]
	v_mfma_f32_16x16x32_bf16 v[76:79], v[64:67], v[132:135], v[80:83]
	v_mfma_f32_16x16x32_bf16 v[164:167], v[68:71], v[100:103], v[148:151]
	v_mfma_f32_16x16x32_bf16 v[148:151], v[68:71], v[144:147], v[76:79]
	v_mfma_f32_16x16x32_bf16 v[76:79], v[196:199], v[132:135], v[88:91]
	v_mfma_f32_16x16x32_bf16 v[144:147], v[200:203], v[144:147], v[76:79]
	v_mfma_f32_16x16x32_bf16 v[76:79], v[64:67], v[204:207], v[92:95]
	v_mfma_f32_16x16x32_bf16 v[132:135], v[68:71], v[216:219], v[76:79]
	v_mfma_f32_16x16x32_bf16 v[76:79], v[196:199], v[204:207], v[128:131]
	v_mfma_f32_16x16x32_bf16 v[128:131], v[200:203], v[216:219], v[76:79]
	v_mfma_f32_16x16x32_bf16 v[76:79], v[64:67], v[220:223], v[116:119]
	v_mfma_f32_16x16x32_bf16 v[116:119], v[68:71], v[224:227], v[76:79]
	v_mfma_f32_16x16x32_bf16 v[76:79], v[196:199], v[220:223], v[112:115]
	v_mfma_f32_16x16x32_bf16 v[112:115], v[200:203], v[224:227], v[76:79]
	s_barrier
; #define PG8_STAGE(bufoff, gbase, voff) do { _Pragma("unroll") for (int _i = 0; _i < 2; ++_i) \
;         __builtin_amdgcn_global_load_lds((const unsigned*)((const char*)(gbase) + (voff)[_i]), (LAS unsigned*)(lds + (bufoff) + ldsw + _i * 8192), 16, 0, 0); } while (0)
; #define PG8_LDA(dst, b, h) do { _Pragma("unroll") for (int m = 0; m < 4; ++m) _Pragma("unroll") for (int k = 0; k < 2; ++k) dst[m][k] = *(const LAS bf16x8*)(lds + PG8_SA(b, h) + aoff + m * 2048 + k * 1024); } while (0)
; #define PG8_MMA(ai, bj, At, Bt) do { __builtin_amdgcn_s_setprio(1); _Pragma("unroll") for (int m = 0; m < 4; ++m) _Pragma("unroll") for (int n = 0; n < 2; ++n) _Pragma("unroll") for (int k = 0; k < 2; ++k) \
;         acc[ai][bj][m][n] = __builtin_amdgcn_mfma_f32_16x16x32_bf16(Bt[n][k], At[m][k], acc[ai][bj][m][n], 0, 0, 0); __builtin_amdgcn_s_setprio(0); } while (0)
; #define PG8_WAIT_V(n) asm volatile("s_waitcnt vmcnt(" #n ")" ::: "memory")
; #define PG8_WAIT_L(n) asm volatile("s_waitcnt lgkmcnt(" #n ")" ::: "memory")
; #define PG8_BAR __builtin_amdgcn_s_barrier()
; #define PG8_SCHED __builtin_amdgcn_sched_barrier(0)
; template <class Sched, class Epi, bool ALIGN_EPI, bool SP2>
; __device__ __forceinline__ void gemm_phase(LAS unsigned char* lds, const int K, const int lda, const int ldb, const Sched& S, const Epi& E) {
;     ...
;             PG8_LDA(At, 1, 1); PG8_STAGE(PG8_SB(1, 0), b3, voffB); PG8_STAGE(PG8_SB(1, 1), b3 + hstepB, voffB); PG8_STAGE(PG8_SA(1, 0), a3, voffA);
;             PG8_WAIT_V(8); PG8_WAIT_L(0); PG8_BAR; PG8_MMA(1, 0, At, B0); PG8_MMA(1, 1, At, B1); PG8_BAR; PG8_SCHED;
	s_add_i32 s8, s51, s88
	v_lshl_add_u64 v[96:97], v[208:209], 0, s[10:11]
	s_mov_b32 m0, s8
	s_nop 1
	ds_read_b128 v[76:79], v213 offset:49152
	ds_read_b128 v[80:83], v213 offset:50176
	ds_read_b128 v[88:91], v213 offset:51200
	ds_read_b128 v[92:95], v213 offset:52224
	ds_read_b128 v[204:207], v213 offset:53248
	ds_read_b128 v[216:219], v213 offset:54272
	ds_read_b128 v[220:223], v213 offset:55296
	ds_read_b128 v[224:227], v213 offset:56320
	global_load_lds_dwordx4 v[96:97], off
	s_add_i32 m0, s8, 0x2000
	s_add_u32 s8, s28, 0x80080
	v_lshl_add_u64 v[96:97], v[228:229], 0, s[10:11]
	s_addc_u32 s9, s29, 0
	s_add_i32 s17, s17, s88
	global_load_lds_dwordx4 v[96:97], off
	s_mov_b32 m0, s17
	s_nop 0
	global_load_lds_dwordx4 v186, s[8:9]
	s_add_i32 m0, s17, 0x2000
	s_nop 0
	global_load_lds_dwordx4 v190, s[8:9]
	v_lshl_add_u64 v[96:97], v[230:231], 0, s[10:11]
	s_mov_b32 m0, s97
	s_nop 0
	global_load_lds_dwordx4 v[96:97], off
	v_lshl_add_u64 v[96:97], v[232:233], 0, s[10:11]
	s_mov_b32 m0, s84
	s_nop 0
	global_load_lds_dwordx4 v[96:97], off
	s_waitcnt vmcnt(8) lgkmcnt(0)
	s_barrier
	v_mfma_f32_16x16x32_bf16 v[96:99], v[48:51], v[76:79], v[108:111]
	v_mfma_f32_16x16x32_bf16 v[108:111], v[52:55], v[80:83], v[96:99]
	v_mfma_f32_16x16x32_bf16 v[96:99], v[56:59], v[76:79], v[104:107]
	v_mfma_f32_16x16x32_bf16 v[84:87], v[48:51], v[88:91], v[84:87]
	v_mfma_f32_16x16x32_bf16 v[72:75], v[56:59], v[88:91], v[72:75]
	v_mfma_f32_16x16x32_bf16 v[28:31], v[48:51], v[204:207], v[28:31]
	v_mfma_f32_16x16x32_bf16 v[24:27], v[56:59], v[204:207], v[24:27]
	v_mfma_f32_16x16x32_bf16 v[12:15], v[48:51], v[220:223], v[12:15]
	v_mfma_f32_16x16x32_bf16 v[8:11], v[56:59], v[220:223], v[8:11]
	v_mfma_f32_16x16x32_bf16 v[104:107], v[60:63], v[80:83], v[96:99]
	v_mfma_f32_16x16x32_bf16 v[84:87], v[52:55], v[92:95], v[84:87]
	v_mfma_f32_16x16x32_bf16 v[72:75], v[60:63], v[92:95], v[72:75]
	v_mfma_f32_16x16x32_bf16 v[28:31], v[52:55], v[216:219], v[28:31]
	v_mfma_f32_16x16x32_bf16 v[24:27], v[60:63], v[216:219], v[24:27]
	v_mfma_f32_16x16x32_bf16 v[12:15], v[52:55], v[224:227], v[12:15]
	v_mfma_f32_16x16x32_bf16 v[8:11], v[60:63], v[224:227], v[8:11]
	v_mfma_f32_16x16x32_bf16 v[32:35], v[64:67], v[76:79], v[32:35]
	v_mfma_f32_16x16x32_bf16 v[100:103], v[68:71], v[80:83], v[32:35]
	v_mfma_f32_16x16x32_bf16 v[32:35], v[196:199], v[76:79], v[36:39]
	v_mfma_f32_16x16x32_bf16 v[96:99], v[200:203], v[80:83], v[32:35]
	v_mfma_f32_16x16x32_bf16 v[32:35], v[64:67], v[88:91], v[44:47]
	v_mfma_f32_16x16x32_bf16 v[44:47], v[68:71], v[92:95], v[32:35]
	v_mfma_f32_16x16x32_bf16 v[32:35], v[196:199], v[88:91], v[40:43]
	v_mfma_f32_16x16x32_bf16 v[20:23], v[64:67], v[204:207], v[20:23]
	v_mfma_f32_16x16x32_bf16 v[16:19], v[196:199], v[204:207], v[16:19]
	v_mfma_f32_16x16x32_bf16 v[4:7], v[64:67], v[220:223], v[4:7]
	v_mfma_f32_16x16x32_bf16 v[0:3], v[196:199], v[220:223], v[0:3]
	v_mfma_f32_16x16x32_bf16 v[40:43], v[200:203], v[92:95], v[32:35]
	v_mfma_f32_16x16x32_bf16 v[20:23], v[68:71], v[216:219], v[20:23]
	v_mfma_f32_16x16x32_bf16 v[16:19], v[200:203], v[216:219], v[16:19]
	v_mfma_f32_16x16x32_bf16 v[4:7], v[68:71], v[224:227], v[4:7]
	v_mfma_f32_16x16x32_bf16 v[0:3], v[200:203], v[224:227], v[0:3]
	s_barrier
	s_add_i32 s7, s7, 2
	s_add_u32 s26, s26, 0x100
	s_addc_u32 s27, s27, 0
	s_add_u32 vcc_hi, vcc_hi, 0x100
	s_addc_u32 s6, s6, 0
	s_cmp_gt_u32 s7, 29

; #define PG8_STAGE(bufoff, gbase, voff) do { _Pragma("unroll") for (int _i = 0; _i < 2; ++_i) \
;         __builtin_amdgcn_global_load_lds((const unsigned*)((const char*)(gbase) + (voff)[_i]), (LAS unsigned*)(lds + (bufoff) + ldsw + _i * 8192), 16, 0, 0); } while (0)
; #define PG8_LDA(dst, b, h) do { _Pragma("unroll") for (int m = 0; m < 4; ++m) _Pragma("unroll") for (int k = 0; k < 2; ++k) dst[m][k] = *(const LAS bf16x8*)(lds + PG8_SA(b, h) + aoff + m * 2048 + k * 1024); } while (0)
; #define PG8_LDB(dst, b, h) do { _Pragma("unroll") for (int n = 0; n < 2; ++n) _Pragma("unroll") for (int k = 0; k < 2; ++k) dst[n][k] = *(const LAS bf16x8*)(lds + PG8_SB(b, h) + boff + n * 2048 + k * 1024); } while (0)
; #define PG8_MMA(ai, bj, At, Bt) do { __builtin_amdgcn_s_setprio(1); _Pragma("unroll") for (int m = 0; m < 4; ++m) _Pragma("unroll") for (int n = 0; n < 2; ++n) _Pragma("unroll") for (int k = 0; k < 2; ++k) \
;         acc[ai][bj][m][n] = __builtin_amdgcn_mfma_f32_16x16x32_bf16(Bt[n][k], At[m][k], acc[ai][bj][m][n], 0, 0, 0); __builtin_amdgcn_s_setprio(0); } while (0)
; #define PG8_WAIT_V(n) asm volatile("s_waitcnt vmcnt(" #n ")" ::: "memory")
; #define PG8_WAIT_L(n) asm volatile("s_waitcnt lgkmcnt(" #n ")" ::: "memory")
; #define PG8_BAR __builtin_amdgcn_s_barrier()
; #define PG8_SCHED __builtin_amdgcn_sched_barrier(0)
; template <class Sched, class Epi, bool ALIGN_EPI, bool SP2>
; __device__ __forceinline__ void gemm_phase(LAS unsigned char* lds, const int K, const int lda, const int ldb, const Sched& S, const Epi& E) {
;     ...
;     f32x4 acc[2][2][4][2];
; #pragma unroll
;     for (int a = 0; a < 2; ++a)
; #pragma unroll
;         for (int b = 0; b < 2; ++b)
; #pragma unroll
;             for (int m = 0; m < 4; ++m)
; #pragma unroll
;                 for (int n = 0; n < 2; ++n) acc[a][b][m][n] = (f32x4){0.f, 0.f, 0.f, 0.f};
;     ...
;             PG8_LDB(B0, 0, 0); PG8_LDB(B1, 0, 1); PG8_SCHED; PG8_LDA(At, 0, 0); PG8_STAGE(PG8_SA(1, 1), a1 + hstepA, voffA);
;             PG8_WAIT_V(8); PG8_WAIT_L(0); PG8_BAR; PG8_MMA(0, 0, At, B0); PG8_MMA(0, 1, At, B1); PG8_BAR; PG8_SCHED;
;             PG8_LDA(At, 0, 1); PG8_STAGE(PG8_SB(0, 0), b2, voffB); PG8_STAGE(PG8_SB(0, 1), b2 + hstepB, voffB); PG8_STAGE(PG8_SA(0, 0), a2, voffA);
;             PG8_WAIT_V(8); PG8_WAIT_L(0); PG8_BAR; PG8_MMA(1, 0, At, B0); PG8_MMA(1, 1, At, B1); PG8_BAR; PG8_SCHED;
.LBB0_944:
	s_add_u32 s36, s36, 0x80080
	s_addc_u32 s37, s37, 0
	s_add_u32 s1, s42, 0x100
	v_mov_b32_e32 v0, 0
	s_addc_u32 s25, s43, 0
	s_mov_b32 s61, -2
	v_mov_b32_e32 v1, v0
	s_waitcnt lgkmcnt(0)
	v_readlane_b32 s98, v255, 13
	s_nop 4
	s_cmp_gt_u32 s98, 3
	s_cbranch_scc1 .Lprio_skip_945
	s_setprio 1
.Lprio_skip_945:
	ds_read_b128 v[52:55], v209
	ds_read_b128 v[56:59], v209 offset:1024
	ds_read_b128 v[64:67], v209 offset:2048
	ds_read_b128 v[68:71], v209 offset:3072
	ds_read_b128 v[72:75], v210
	ds_read_b128 v[76:79], v210 offset:1024
	ds_read_b128 v[88:91], v210 offset:2048
	ds_read_b128 v[92:95], v210 offset:3072
	s_add_u32 s42, s36, 0xfff80080
	s_addc_u32 s43, s37, -1
	s_cmp_eq_u32 s61, 28
	s_cselect_b32 s45, s27, s43
	s_cselect_b32 s44, s26, s42
	s_cselect_b32 s43, s29, s25
	s_cselect_b32 s42, s28, s1
	s_add_i32 m0, s21, 0xc000
	ds_read_b128 v[160:163], v211
	ds_read_b128 v[164:167], v211 offset:1024
	ds_read_b128 v[168:171], v211 offset:2048
	ds_read_b128 v[172:175], v211 offset:3072
	ds_read_b128 v[190:193], v211 offset:4096
	ds_read_b128 v[194:197], v211 offset:5120
	ds_read_b128 v[198:201], v211 offset:6144
	ds_read_b128 v[202:205], v211 offset:7168
	global_load_lds_dwordx4 v186, s[36:37]
	s_add_i32 m0, s21, 0xe000
	s_nop 0
	global_load_lds_dwordx4 v188, s[36:37]
	s_waitcnt vmcnt(8) lgkmcnt(0)
	s_barrier
	v_mfma_f32_16x16x32_bf16 v[156:159], v[52:55], v[160:163], 0
	v_mfma_f32_16x16x32_bf16 v[152:155], v[64:67], v[160:163], 0
	v_mfma_f32_16x16x32_bf16 v[140:143], v[52:55], v[168:171], 0
	v_mfma_f32_16x16x32_bf16 v[136:139], v[64:67], v[168:171], 0
	v_mfma_f32_16x16x32_bf16 v[124:127], v[52:55], v[190:193], 0
	v_mfma_f32_16x16x32_bf16 v[120:123], v[64:67], v[190:193], 0
	v_mfma_f32_16x16x32_bf16 v[108:111], v[52:55], v[198:201], 0
	v_mfma_f32_16x16x32_bf16 v[104:107], v[64:67], v[198:201], 0
	v_mfma_f32_16x16x32_bf16 v[156:159], v[56:59], v[164:167], v[156:159]
	v_mfma_f32_16x16x32_bf16 v[152:155], v[68:71], v[164:167], v[152:155]
	v_mfma_f32_16x16x32_bf16 v[140:143], v[56:59], v[172:175], v[140:143]
	v_mfma_f32_16x16x32_bf16 v[136:139], v[68:71], v[172:175], v[136:139]
	v_mfma_f32_16x16x32_bf16 v[124:127], v[56:59], v[194:197], v[124:127]
	v_mfma_f32_16x16x32_bf16 v[120:123], v[68:71], v[194:197], v[120:123]
	v_mfma_f32_16x16x32_bf16 v[108:111], v[56:59], v[202:205], v[108:111]
	v_mfma_f32_16x16x32_bf16 v[104:107], v[68:71], v[202:205], v[104:107]
	v_mfma_f32_16x16x32_bf16 v[148:151], v[72:75], v[160:163], 0
	v_mfma_f32_16x16x32_bf16 v[144:147], v[88:91], v[160:163], 0
	v_mfma_f32_16x16x32_bf16 v[132:135], v[72:75], v[168:171], 0
	v_mfma_f32_16x16x32_bf16 v[128:131], v[88:91], v[168:171], 0
	v_mfma_f32_16x16x32_bf16 v[116:119], v[72:75], v[190:193], 0
	v_mfma_f32_16x16x32_bf16 v[112:115], v[88:91], v[190:193], 0
	v_mfma_f32_16x16x32_bf16 v[100:103], v[72:75], v[198:201], 0
	v_mfma_f32_16x16x32_bf16 v[96:99], v[88:91], v[198:201], 0
	v_mfma_f32_16x16x32_bf16 v[148:151], v[76:79], v[164:167], v[148:151]
	v_mfma_f32_16x16x32_bf16 v[144:147], v[92:95], v[164:167], v[144:147]
	v_mfma_f32_16x16x32_bf16 v[132:135], v[76:79], v[172:175], v[132:135]
	v_mfma_f32_16x16x32_bf16 v[128:131], v[92:95], v[172:175], v[128:131]
	v_mfma_f32_16x16x32_bf16 v[116:119], v[76:79], v[194:197], v[116:119]
	v_mfma_f32_16x16x32_bf16 v[112:115], v[92:95], v[194:197], v[112:115]
	v_mfma_f32_16x16x32_bf16 v[100:103], v[76:79], v[202:205], v[100:103]
	v_mfma_f32_16x16x32_bf16 v[96:99], v[92:95], v[202:205], v[96:99]
	s_barrier
	s_add_i32 s62, s50, s19
	v_lshl_add_u64 v[206:207], s[42:43], 0, v[182:183]
	s_mov_b32 m0, s62
	ds_read_b128 v[160:163], v211 offset:16384
	ds_read_b128 v[164:167], v211 offset:17408
	ds_read_b128 v[168:171], v211 offset:18432
	ds_read_b128 v[172:175], v211 offset:19456
	ds_read_b128 v[190:193], v211 offset:20480
	ds_read_b128 v[194:197], v211 offset:21504
	ds_read_b128 v[198:201], v211 offset:22528
	ds_read_b128 v[202:205], v211 offset:23552
	global_load_lds_dwordx4 v[206:207], off
	s_add_i32 m0, s62, 0x2000
	s_add_u32 s62, s42, 0x80000
	v_lshl_add_u64 v[214:215], s[42:43], 0, v[184:185]
	s_addc_u32 s63, s43, 0
	s_add_i32 s64, s51, s19
	global_load_lds_dwordx4 v[214:215], off
	s_mov_b32 m0, s64
	v_lshl_add_u64 v[218:219], s[44:45], 0, v[184:185]
	global_load_lds_dwordx4 v182, s[62:63]
	s_add_i32 m0, s64, 0x2000
	s_nop 0
	global_load_lds_dwordx4 v184, s[62:63]
	v_lshl_add_u64 v[216:217], s[44:45], 0, v[182:183]
	s_mov_b32 m0, s21
	s_nop 0
	global_load_lds_dwordx4 v[216:217], off
	s_mov_b32 m0, s33
	s_nop 0
	global_load_lds_dwordx4 v[218:219], off
	s_waitcnt vmcnt(8) lgkmcnt(0)
	s_barrier
	v_mfma_f32_16x16x32_bf16 v[84:87], v[52:55], v[160:163], 0
	v_mfma_f32_16x16x32_bf16 v[80:83], v[64:67], v[160:163], 0
	v_mfma_f32_16x16x32_bf16 v[44:47], v[52:55], v[168:171], 0
	v_mfma_f32_16x16x32_bf16 v[40:43], v[64:67], v[168:171], 0
	v_mfma_f32_16x16x32_bf16 v[28:31], v[52:55], v[190:193], 0
	v_mfma_f32_16x16x32_bf16 v[24:27], v[64:67], v[190:193], 0
	v_mfma_f32_16x16x32_bf16 v[12:15], v[52:55], v[198:201], 0
	v_mfma_f32_16x16x32_bf16 v[8:11], v[64:67], v[198:201], 0
	v_mfma_f32_16x16x32_bf16 v[84:87], v[56:59], v[164:167], v[84:87]
	v_mfma_f32_16x16x32_bf16 v[80:83], v[68:71], v[164:167], v[80:83]
	v_mfma_f32_16x16x32_bf16 v[44:47], v[56:59], v[172:175], v[44:47]
	v_mfma_f32_16x16x32_bf16 v[40:43], v[68:71], v[172:175], v[40:43]
	v_mfma_f32_16x16x32_bf16 v[28:31], v[56:59], v[194:197], v[28:31]
	v_mfma_f32_16x16x32_bf16 v[24:27], v[68:71], v[194:197], v[24:27]
	v_mfma_f32_16x16x32_bf16 v[12:15], v[56:59], v[202:205], v[12:15]
	v_mfma_f32_16x16x32_bf16 v[8:11], v[68:71], v[202:205], v[8:11]
	v_mfma_f32_16x16x32_bf16 v[48:51], v[88:91], v[160:163], 0
	v_mfma_f32_16x16x32_bf16 v[36:39], v[72:75], v[168:171], 0
	v_mfma_f32_16x16x32_bf16 v[32:35], v[88:91], v[168:171], 0
	v_mfma_f32_16x16x32_bf16 v[20:23], v[72:75], v[190:193], 0
	v_mfma_f32_16x16x32_bf16 v[16:19], v[88:91], v[190:193], 0
	v_mfma_f32_16x16x32_bf16 v[4:7], v[72:75], v[198:201], 0
	v_mfma_f32_16x16x32_bf16 v[0:3], v[88:91], v[198:201], 0
	v_mfma_f32_16x16x32_bf16 v[52:55], v[72:75], v[160:163], 0
	v_mfma_f32_16x16x32_bf16 v[48:51], v[92:95], v[164:167], v[48:51]
	v_mfma_f32_16x16x32_bf16 v[36:39], v[76:79], v[172:175], v[36:39]
	v_mfma_f32_16x16x32_bf16 v[32:35], v[92:95], v[172:175], v[32:35]
	v_mfma_f32_16x16x32_bf16 v[20:23], v[76:79], v[194:197], v[20:23]
	v_mfma_f32_16x16x32_bf16 v[16:19], v[92:95], v[194:197], v[16:19]
	v_mfma_f32_16x16x32_bf16 v[4:7], v[76:79], v[202:205], v[4:7]
	v_mfma_f32_16x16x32_bf16 v[0:3], v[92:95], v[202:205], v[0:3]
	v_mfma_f32_16x16x32_bf16 v[52:55], v[76:79], v[164:167], v[52:55]
	s_barrier
; #define PG8_STAGE(bufoff, gbase, voff) do { _Pragma("unroll") for (int _i = 0; _i < 2; ++_i) \
;         __builtin_amdgcn_global_load_lds((const unsigned*)((const char*)(gbase) + (voff)[_i]), (LAS unsigned*)(lds + (bufoff) + ldsw + _i * 8192), 16, 0, 0); } while (0)
; #define PG8_LDA(dst, b, h) do { _Pragma("unroll") for (int m = 0; m < 4; ++m) _Pragma("unroll") for (int k = 0; k < 2; ++k) dst[m][k] = *(const LAS bf16x8*)(lds + PG8_SA(b, h) + aoff + m * 2048 + k * 1024); } while (0)
; #define PG8_LDB(dst, b, h) do { _Pragma("unroll") for (int n = 0; n < 2; ++n) _Pragma("unroll") for (int k = 0; k < 2; ++k) dst[n][k] = *(const LAS bf16x8*)(lds + PG8_SB(b, h) + boff + n * 2048 + k * 1024); } while (0)
; #define PG8_MMA(ai, bj, At, Bt) do { __builtin_amdgcn_s_setprio(1); _Pragma("unroll") for (int m = 0; m < 4; ++m) _Pragma("unroll") for (int n = 0; n < 2; ++n) _Pragma("unroll") for (int k = 0; k < 2; ++k) \
;         acc[ai][bj][m][n] = __builtin_amdgcn_mfma_f32_16x16x32_bf16(Bt[n][k], At[m][k], acc[ai][bj][m][n], 0, 0, 0); __builtin_amdgcn_s_setprio(0); } while (0)
; #define PG8_WAIT_V(n) asm volatile("s_waitcnt vmcnt(" #n ")" ::: "memory")
; #define PG8_WAIT_L(n) asm volatile("s_waitcnt lgkmcnt(" #n ")" ::: "memory")
; #define PG8_BAR __builtin_amdgcn_s_barrier()
; #define PG8_SCHED __builtin_amdgcn_sched_barrier(0)
; template <class Sched, class Epi, bool ALIGN_EPI, bool SP2>
; __device__ __forceinline__ void gemm_phase(LAS unsigned char* lds, const int K, const int lda, const int ldb, const Sched& S, const Epi& E) {
;     ...
;             PG8_LDB(B0, 1, 0); PG8_LDB(B1, 1, 1); PG8_SCHED; PG8_LDA(At, 1, 0); PG8_STAGE(PG8_SA(0, 1), a2 + hstepA, voffA);
;             PG8_WAIT_V(8); PG8_WAIT_L(0); PG8_BAR; PG8_MMA(0, 0, At, B0); PG8_MMA(0, 1, At, B1); PG8_BAR; PG8_SCHED;
;             PG8_LDA(At, 1, 1); PG8_STAGE(PG8_SB(1, 0), b3, voffB); PG8_STAGE(PG8_SB(1, 1), b3 + hstepB, voffB); PG8_STAGE(PG8_SA(1, 0), a3, voffA);
;             PG8_WAIT_V(8); PG8_WAIT_L(0); PG8_BAR; PG8_MMA(1, 0, At, B0); PG8_MMA(1, 1, At, B1); PG8_BAR; PG8_SCHED;
	s_add_i32 s62, 0, 0x18000
	s_add_i32 s63, 0, 0x1c000
	v_add_u32_e32 v68, s62, v181
	v_add_u32_e32 v92, s63, v181
	ds_read_b128 v[56:59], v68
	ds_read_b128 v[60:63], v68 offset:1024
	ds_read_b128 v[64:67], v68 offset:2048
	ds_read_b128 v[68:71], v68 offset:3072
	ds_read_b128 v[72:75], v92
	ds_read_b128 v[76:79], v92 offset:1024
	ds_read_b128 v[88:91], v92 offset:2048
	ds_read_b128 v[92:95], v92 offset:3072
	s_add_u32 s44, s44, 0x80000
	s_addc_u32 s45, s45, 0
	s_mov_b32 m0, s35
	ds_read_b128 v[160:163], v211 offset:32768
	ds_read_b128 v[164:167], v211 offset:33792
	ds_read_b128 v[168:171], v211 offset:34816
	ds_read_b128 v[172:175], v211 offset:35840
	ds_read_b128 v[190:193], v211 offset:36864
	ds_read_b128 v[194:197], v211 offset:37888
	ds_read_b128 v[198:201], v211 offset:38912
	ds_read_b128 v[202:205], v211 offset:39936
	global_load_lds_dwordx4 v182, s[44:45]
	s_mov_b32 m0, s46
	s_nop 0
	global_load_lds_dwordx4 v184, s[44:45]
	s_waitcnt vmcnt(8) lgkmcnt(0)
	s_barrier
	v_mfma_f32_16x16x32_bf16 v[156:159], v[56:59], v[160:163], v[156:159]
	v_mfma_f32_16x16x32_bf16 v[152:155], v[64:67], v[160:163], v[152:155]
	v_mfma_f32_16x16x32_bf16 v[140:143], v[56:59], v[168:171], v[140:143]
	v_mfma_f32_16x16x32_bf16 v[136:139], v[64:67], v[168:171], v[136:139]
	v_mfma_f32_16x16x32_bf16 v[124:127], v[56:59], v[190:193], v[124:127]
	v_mfma_f32_16x16x32_bf16 v[120:123], v[64:67], v[190:193], v[120:123]
	v_mfma_f32_16x16x32_bf16 v[108:111], v[56:59], v[198:201], v[108:111]
	v_mfma_f32_16x16x32_bf16 v[104:107], v[64:67], v[198:201], v[104:107]
	v_mfma_f32_16x16x32_bf16 v[156:159], v[60:63], v[164:167], v[156:159]
	v_mfma_f32_16x16x32_bf16 v[152:155], v[68:71], v[164:167], v[152:155]
	v_mfma_f32_16x16x32_bf16 v[140:143], v[60:63], v[172:175], v[140:143]
	v_mfma_f32_16x16x32_bf16 v[136:139], v[68:71], v[172:175], v[136:139]
	v_mfma_f32_16x16x32_bf16 v[124:127], v[60:63], v[194:197], v[124:127]
	v_mfma_f32_16x16x32_bf16 v[120:123], v[68:71], v[194:197], v[120:123]
	v_mfma_f32_16x16x32_bf16 v[108:111], v[60:63], v[202:205], v[108:111]
	v_mfma_f32_16x16x32_bf16 v[104:107], v[68:71], v[202:205], v[104:107]
	v_mfma_f32_16x16x32_bf16 v[148:151], v[72:75], v[160:163], v[148:151]
	v_mfma_f32_16x16x32_bf16 v[144:147], v[88:91], v[160:163], v[144:147]
	v_mfma_f32_16x16x32_bf16 v[132:135], v[72:75], v[168:171], v[132:135]
	v_mfma_f32_16x16x32_bf16 v[128:131], v[88:91], v[168:171], v[128:131]
	v_mfma_f32_16x16x32_bf16 v[116:119], v[72:75], v[190:193], v[116:119]
	v_mfma_f32_16x16x32_bf16 v[112:115], v[88:91], v[190:193], v[112:115]
	v_mfma_f32_16x16x32_bf16 v[100:103], v[72:75], v[198:201], v[100:103]
	v_mfma_f32_16x16x32_bf16 v[96:99], v[88:91], v[198:201], v[96:99]
	v_mfma_f32_16x16x32_bf16 v[148:151], v[76:79], v[164:167], v[148:151]
	v_mfma_f32_16x16x32_bf16 v[144:147], v[92:95], v[164:167], v[144:147]
	v_mfma_f32_16x16x32_bf16 v[132:135], v[76:79], v[172:175], v[132:135]
	v_mfma_f32_16x16x32_bf16 v[128:131], v[92:95], v[172:175], v[128:131]
	v_mfma_f32_16x16x32_bf16 v[116:119], v[76:79], v[194:197], v[116:119]
	v_mfma_f32_16x16x32_bf16 v[112:115], v[92:95], v[194:197], v[112:115]
	v_mfma_f32_16x16x32_bf16 v[100:103], v[76:79], v[202:205], v[100:103]
	v_mfma_f32_16x16x32_bf16 v[96:99], v[92:95], v[202:205], v[96:99]
	s_barrier
	s_add_i32 s44, s62, s19
	v_lshl_add_u64 v[206:207], v[206:207], 0, s[14:15]
	s_mov_b32 m0, s44
	ds_read_b128 v[160:163], v211 offset:49152
	ds_read_b128 v[164:167], v211 offset:50176
	ds_read_b128 v[168:171], v211 offset:51200
	ds_read_b128 v[172:175], v211 offset:52224
	ds_read_b128 v[190:193], v211 offset:53248
	ds_read_b128 v[194:197], v211 offset:54272
	ds_read_b128 v[198:201], v211 offset:55296
	ds_read_b128 v[202:205], v211 offset:56320
	global_load_lds_dwordx4 v[206:207], off
	s_add_i32 m0, s44, 0x2000
	s_add_u32 s42, s42, 0x80080
	v_lshl_add_u64 v[206:207], v[214:215], 0, s[14:15]
	s_addc_u32 s43, s43, 0
	s_add_i32 s44, s63, s19
	global_load_lds_dwordx4 v[206:207], off
	s_mov_b32 m0, s44
	s_nop 0
	global_load_lds_dwordx4 v182, s[42:43]
	s_add_i32 m0, s44, 0x2000
	s_nop 0
	global_load_lds_dwordx4 v184, s[42:43]
	v_lshl_add_u64 v[206:207], v[216:217], 0, s[14:15]
	s_mov_b32 m0, s48
	s_nop 0
	global_load_lds_dwordx4 v[206:207], off
	v_lshl_add_u64 v[206:207], v[218:219], 0, s[14:15]
	s_mov_b32 m0, s49
	s_nop 0
	global_load_lds_dwordx4 v[206:207], off
	s_waitcnt vmcnt(8) lgkmcnt(0)
	s_barrier
	v_mfma_f32_16x16x32_bf16 v[84:87], v[56:59], v[160:163], v[84:87]
	v_mfma_f32_16x16x32_bf16 v[80:83], v[64:67], v[160:163], v[80:83]
	v_mfma_f32_16x16x32_bf16 v[44:47], v[56:59], v[168:171], v[44:47]
	v_mfma_f32_16x16x32_bf16 v[40:43], v[64:67], v[168:171], v[40:43]
	v_mfma_f32_16x16x32_bf16 v[28:31], v[56:59], v[190:193], v[28:31]
	v_mfma_f32_16x16x32_bf16 v[24:27], v[64:67], v[190:193], v[24:27]
	v_mfma_f32_16x16x32_bf16 v[12:15], v[56:59], v[198:201], v[12:15]
	v_mfma_f32_16x16x32_bf16 v[8:11], v[64:67], v[198:201], v[8:11]
	v_mfma_f32_16x16x32_bf16 v[84:87], v[60:63], v[164:167], v[84:87]
	v_mfma_f32_16x16x32_bf16 v[80:83], v[68:71], v[164:167], v[80:83]
	v_mfma_f32_16x16x32_bf16 v[44:47], v[60:63], v[172:175], v[44:47]
	v_mfma_f32_16x16x32_bf16 v[40:43], v[68:71], v[172:175], v[40:43]
	v_mfma_f32_16x16x32_bf16 v[28:31], v[60:63], v[194:197], v[28:31]
	v_mfma_f32_16x16x32_bf16 v[24:27], v[68:71], v[194:197], v[24:27]
	v_mfma_f32_16x16x32_bf16 v[12:15], v[60:63], v[202:205], v[12:15]
	v_mfma_f32_16x16x32_bf16 v[8:11], v[68:71], v[202:205], v[8:11]
	v_mfma_f32_16x16x32_bf16 v[52:55], v[72:75], v[160:163], v[52:55]
	v_mfma_f32_16x16x32_bf16 v[48:51], v[88:91], v[160:163], v[48:51]
	v_mfma_f32_16x16x32_bf16 v[36:39], v[72:75], v[168:171], v[36:39]
	v_mfma_f32_16x16x32_bf16 v[32:35], v[88:91], v[168:171], v[32:35]
	v_mfma_f32_16x16x32_bf16 v[20:23], v[72:75], v[190:193], v[20:23]
	v_mfma_f32_16x16x32_bf16 v[16:19], v[88:91], v[190:193], v[16:19]
	v_mfma_f32_16x16x32_bf16 v[4:7], v[72:75], v[198:201], v[4:7]
	v_mfma_f32_16x16x32_bf16 v[0:3], v[88:91], v[198:201], v[0:3]
	v_mfma_f32_16x16x32_bf16 v[60:63], v[76:79], v[164:167], v[52:55]
	v_mfma_f32_16x16x32_bf16 v[48:51], v[92:95], v[164:167], v[48:51]
	v_mfma_f32_16x16x32_bf16 v[36:39], v[76:79], v[172:175], v[36:39]
	v_mfma_f32_16x16x32_bf16 v[32:35], v[92:95], v[172:175], v[32:35]
	v_mfma_f32_16x16x32_bf16 v[20:23], v[76:79], v[194:197], v[20:23]
	v_mfma_f32_16x16x32_bf16 v[16:19], v[92:95], v[194:197], v[16:19]
	v_mfma_f32_16x16x32_bf16 v[4:7], v[76:79], v[202:205], v[4:7]
	v_mfma_f32_16x16x32_bf16 v[0:3], v[92:95], v[202:205], v[0:3]
	s_barrier
	s_add_i32 s61, s61, 2
	s_add_u32 s36, s36, 0x100
	s_addc_u32 s37, s37, 0
	s_add_u32 s1, s1, 0x100
	s_addc_u32 s25, s25, 0
	s_cmp_gt_u32 s61, 29

; #define PG8_STAGE(bufoff, gbase, voff) do { _Pragma("unroll") for (int _i = 0; _i < 2; ++_i) \
;         __builtin_amdgcn_global_load_lds((const unsigned*)((const char*)(gbase) + (voff)[_i]), (LAS unsigned*)(lds + (bufoff) + ldsw + _i * 8192), 16, 0, 0); } while (0)
; #define PG8_LDA(dst, b, h) do { _Pragma("unroll") for (int m = 0; m < 4; ++m) _Pragma("unroll") for (int k = 0; k < 2; ++k) dst[m][k] = *(const LAS bf16x8*)(lds + PG8_SA(b, h) + aoff + m * 2048 + k * 1024); } while (0)
; #define PG8_LDB(dst, b, h) do { _Pragma("unroll") for (int n = 0; n < 2; ++n) _Pragma("unroll") for (int k = 0; k < 2; ++k) dst[n][k] = *(const LAS bf16x8*)(lds + PG8_SB(b, h) + boff + n * 2048 + k * 1024); } while (0)
; #define PG8_MMA(ai, bj, At, Bt) do { __builtin_amdgcn_s_setprio(1); _Pragma("unroll") for (int m = 0; m < 4; ++m) _Pragma("unroll") for (int n = 0; n < 2; ++n) _Pragma("unroll") for (int k = 0; k < 2; ++k) \
;         acc[ai][bj][m][n] = __builtin_amdgcn_mfma_f32_16x16x32_bf16(Bt[n][k], At[m][k], acc[ai][bj][m][n], 0, 0, 0); __builtin_amdgcn_s_setprio(0); } while (0)
; #define PG8_WAIT_V(n) asm volatile("s_waitcnt vmcnt(" #n ")" ::: "memory")
; #define PG8_WAIT_L(n) asm volatile("s_waitcnt lgkmcnt(" #n ")" ::: "memory")
; #define PG8_BAR __builtin_amdgcn_s_barrier()
; #define PG8_SCHED __builtin_amdgcn_sched_barrier(0)
; template <class Sched, class Epi, bool ALIGN_EPI, bool SP2>
; __device__ __forceinline__ void gemm_phase(LAS unsigned char* lds, const int K, const int lda, const int ldb, const Sched& S, const Epi& E) {
;     ...
;     f32x4 acc[2][2][4][2];
; #pragma unroll
;     for (int a = 0; a < 2; ++a)
; #pragma unroll
;         for (int b = 0; b < 2; ++b)
; #pragma unroll
;             for (int m = 0; m < 4; ++m)
; #pragma unroll
;                 for (int n = 0; n < 2; ++n) acc[a][b][m][n] = (f32x4){0.f, 0.f, 0.f, 0.f};
;     ...
;             PG8_LDB(B0, 0, 0); PG8_LDB(B1, 0, 1); PG8_SCHED; PG8_LDA(At, 0, 0); PG8_STAGE(PG8_SA(1, 1), a1 + hstepA, voffA);
;             PG8_WAIT_V(8); PG8_WAIT_L(0); PG8_BAR; PG8_MMA(0, 0, At, B0); PG8_MMA(0, 1, At, B1); PG8_BAR; PG8_SCHED;
;             PG8_LDA(At, 0, 1); PG8_STAGE(PG8_SB(0, 0), b2, voffB); PG8_STAGE(PG8_SB(0, 1), b2 + hstepB, voffB); PG8_STAGE(PG8_SA(0, 0), a2, voffA);
;             PG8_WAIT_V(8); PG8_WAIT_L(0); PG8_BAR; PG8_MMA(1, 0, At, B0); PG8_MMA(1, 1, At, B1); PG8_BAR; PG8_SCHED;
.LBB0_1036:
	s_add_u32 s36, s36, 0x80080
	s_addc_u32 s37, s37, 0
	s_add_u32 s25, s42, 0x100
	v_mov_b32_e32 v4, 0
	s_addc_u32 s56, s43, 0
	s_mov_b32 s57, -2
	v_readlane_b32 s98, v255, 13
	s_nop 4
	s_cmp_gt_u32 s98, 3
	s_cbranch_scc1 .Lprio_skip_1037
	s_setprio 1
.Lprio_skip_1037:
	ds_read_b128 v[64:67], v183
	ds_read_b128 v[68:71], v183 offset:1024
	ds_read_b128 v[72:75], v183 offset:2048
	ds_read_b128 v[76:79], v183 offset:3072
	ds_read_b128 v[144:147], v184
	ds_read_b128 v[160:163], v184 offset:1024
	ds_read_b128 v[164:167], v184 offset:2048
	ds_read_b128 v[168:171], v184 offset:3072
	s_add_u32 s42, s36, 0xfff80080
	s_addc_u32 s43, s37, -1
	s_cmp_eq_u32 s57, 28
	s_cselect_b32 s45, s27, s43
	s_cselect_b32 s44, s26, s42
	s_cselect_b32 s43, s29, s56
	s_cselect_b32 s42, s28, s25
	s_add_i32 m0, s33, 0xc000
	ds_read_b128 v[172:175], v185
	ds_read_b128 v[188:191], v185 offset:1024
	ds_read_b128 v[192:195], v185 offset:2048
	ds_read_b128 v[196:199], v185 offset:3072
	ds_read_b128 v[200:203], v185 offset:4096
	ds_read_b128 v[204:207], v185 offset:5120
	ds_read_b128 v[208:211], v185 offset:6144
	ds_read_b128 v[212:215], v185 offset:7168
	global_load_lds_dwordx4 v156, s[36:37]
	s_add_i32 m0, s33, 0xe000
	s_nop 0
	global_load_lds_dwordx4 v158, s[36:37]
	s_waitcnt vmcnt(8) lgkmcnt(0)
	s_barrier
	v_mfma_f32_16x16x32_bf16 v[140:143], v[64:67], v[172:175], 0
	v_mfma_f32_16x16x32_bf16 v[136:139], v[72:75], v[172:175], 0
	v_mfma_f32_16x16x32_bf16 v[124:127], v[64:67], v[192:195], 0
	v_mfma_f32_16x16x32_bf16 v[120:123], v[72:75], v[192:195], 0
	v_mfma_f32_16x16x32_bf16 v[108:111], v[64:67], v[200:203], 0
	v_mfma_f32_16x16x32_bf16 v[104:107], v[72:75], v[200:203], 0
	v_mfma_f32_16x16x32_bf16 v[92:95], v[64:67], v[208:211], 0
	v_mfma_f32_16x16x32_bf16 v[88:91], v[72:75], v[208:211], 0
	v_mfma_f32_16x16x32_bf16 v[140:143], v[68:71], v[188:191], v[140:143]
	v_mfma_f32_16x16x32_bf16 v[136:139], v[76:79], v[188:191], v[136:139]
	v_mfma_f32_16x16x32_bf16 v[124:127], v[68:71], v[196:199], v[124:127]
	v_mfma_f32_16x16x32_bf16 v[120:123], v[76:79], v[196:199], v[120:123]
	v_mfma_f32_16x16x32_bf16 v[108:111], v[68:71], v[204:207], v[108:111]
	v_mfma_f32_16x16x32_bf16 v[104:107], v[76:79], v[204:207], v[104:107]
	v_mfma_f32_16x16x32_bf16 v[92:95], v[68:71], v[212:215], v[92:95]
	v_mfma_f32_16x16x32_bf16 v[88:91], v[76:79], v[212:215], v[88:91]
	v_mfma_f32_16x16x32_bf16 v[132:135], v[144:147], v[172:175], 0
	v_mfma_f32_16x16x32_bf16 v[128:131], v[164:167], v[172:175], 0
	v_mfma_f32_16x16x32_bf16 v[116:119], v[144:147], v[192:195], 0
	v_mfma_f32_16x16x32_bf16 v[112:115], v[164:167], v[192:195], 0
	v_mfma_f32_16x16x32_bf16 v[100:103], v[144:147], v[200:203], 0
	v_mfma_f32_16x16x32_bf16 v[96:99], v[164:167], v[200:203], 0
	v_mfma_f32_16x16x32_bf16 v[84:87], v[144:147], v[208:211], 0
	v_mfma_f32_16x16x32_bf16 v[80:83], v[164:167], v[208:211], 0
	v_mfma_f32_16x16x32_bf16 v[132:135], v[160:163], v[188:191], v[132:135]
	v_mfma_f32_16x16x32_bf16 v[128:131], v[168:171], v[188:191], v[128:131]
	v_mfma_f32_16x16x32_bf16 v[116:119], v[160:163], v[196:199], v[116:119]
	v_mfma_f32_16x16x32_bf16 v[112:115], v[168:171], v[196:199], v[112:115]
	v_mfma_f32_16x16x32_bf16 v[100:103], v[160:163], v[204:207], v[100:103]
	v_mfma_f32_16x16x32_bf16 v[96:99], v[168:171], v[204:207], v[96:99]
	v_mfma_f32_16x16x32_bf16 v[84:87], v[160:163], v[212:215], v[84:87]
	v_mfma_f32_16x16x32_bf16 v[80:83], v[168:171], v[212:215], v[80:83]
	s_barrier
	s_add_i32 s58, s51, s21
	v_lshl_add_u64 v[216:217], s[42:43], 0, v[150:151]
	s_mov_b32 m0, s58
	ds_read_b128 v[172:175], v185 offset:16384
	ds_read_b128 v[188:191], v185 offset:17408
	ds_read_b128 v[192:195], v185 offset:18432
	ds_read_b128 v[196:199], v185 offset:19456
	ds_read_b128 v[200:203], v185 offset:20480
	ds_read_b128 v[204:207], v185 offset:21504
	ds_read_b128 v[208:211], v185 offset:22528
	ds_read_b128 v[212:215], v185 offset:23552
	global_load_lds_dwordx4 v[216:217], off
	s_add_i32 m0, s58, 0x2000
	s_add_u32 s58, s42, 0x80000
	v_lshl_add_u64 v[218:219], s[42:43], 0, v[154:155]
	s_addc_u32 s59, s43, 0
	s_add_i32 s60, s52, s21
	global_load_lds_dwordx4 v[218:219], off
	s_mov_b32 m0, s60
	v_lshl_add_u64 v[222:223], s[44:45], 0, v[152:153]
	global_load_lds_dwordx4 v150, s[58:59]
	s_add_i32 m0, s60, 0x2000
	s_nop 0
	global_load_lds_dwordx4 v154, s[58:59]
	v_lshl_add_u64 v[220:221], s[44:45], 0, v[148:149]
	s_mov_b32 m0, s33
	s_nop 0
	global_load_lds_dwordx4 v[220:221], off
	s_mov_b32 m0, s35
	s_nop 0
	global_load_lds_dwordx4 v[222:223], off
	s_waitcnt vmcnt(8) lgkmcnt(0)
	s_barrier
	v_mfma_f32_16x16x32_bf16 v[60:63], v[64:67], v[172:175], 0
	v_mfma_f32_16x16x32_bf16 v[56:59], v[72:75], v[172:175], 0
	v_mfma_f32_16x16x32_bf16 v[44:47], v[64:67], v[192:195], 0
	v_mfma_f32_16x16x32_bf16 v[40:43], v[72:75], v[192:195], 0
	v_mfma_f32_16x16x32_bf16 v[24:27], v[64:67], v[200:203], 0
	v_mfma_f32_16x16x32_bf16 v[20:23], v[72:75], v[200:203], 0
	v_mfma_f32_16x16x32_bf16 v[8:11], v[64:67], v[208:211], 0
	v_mfma_f32_16x16x32_bf16 v[0:3], v[72:75], v[208:211], 0
	v_mfma_f32_16x16x32_bf16 v[60:63], v[68:71], v[188:191], v[60:63]
	v_mfma_f32_16x16x32_bf16 v[56:59], v[76:79], v[188:191], v[56:59]
	v_mfma_f32_16x16x32_bf16 v[44:47], v[68:71], v[196:199], v[44:47]
	v_mfma_f32_16x16x32_bf16 v[40:43], v[76:79], v[196:199], v[40:43]
	v_mfma_f32_16x16x32_bf16 v[24:27], v[68:71], v[204:207], v[24:27]
	v_mfma_f32_16x16x32_bf16 v[20:23], v[76:79], v[204:207], v[20:23]
	v_mfma_f32_16x16x32_bf16 v[8:11], v[68:71], v[212:215], v[8:11]
	v_mfma_f32_16x16x32_bf16 v[0:3], v[76:79], v[212:215], v[0:3]
	v_mfma_f32_16x16x32_bf16 v[52:55], v[144:147], v[172:175], 0
	v_mfma_f32_16x16x32_bf16 v[48:51], v[164:167], v[172:175], 0
	v_mfma_f32_16x16x32_bf16 v[36:39], v[144:147], v[192:195], 0
	v_mfma_f32_16x16x32_bf16 v[32:35], v[164:167], v[192:195], 0
	v_mfma_f32_16x16x32_bf16 v[28:31], v[144:147], v[200:203], 0
	v_mfma_f32_16x16x32_bf16 v[16:19], v[164:167], v[200:203], 0
	v_mfma_f32_16x16x32_bf16 v[12:15], v[144:147], v[208:211], 0
	v_mfma_f32_16x16x32_bf16 v[4:7], v[164:167], v[208:211], 0
	v_mfma_f32_16x16x32_bf16 v[52:55], v[160:163], v[188:191], v[52:55]
	v_mfma_f32_16x16x32_bf16 v[48:51], v[168:171], v[188:191], v[48:51]
	v_mfma_f32_16x16x32_bf16 v[36:39], v[160:163], v[196:199], v[36:39]
	v_mfma_f32_16x16x32_bf16 v[32:35], v[168:171], v[196:199], v[32:35]
	v_mfma_f32_16x16x32_bf16 v[28:31], v[160:163], v[204:207], v[28:31]
	v_mfma_f32_16x16x32_bf16 v[16:19], v[168:171], v[204:207], v[16:19]
	v_mfma_f32_16x16x32_bf16 v[12:15], v[160:163], v[212:215], v[12:15]
	v_mfma_f32_16x16x32_bf16 v[4:7], v[168:171], v[212:215], v[4:7]
	s_barrier
; #define PG8_STAGE(bufoff, gbase, voff) do { _Pragma("unroll") for (int _i = 0; _i < 2; ++_i) \
;         __builtin_amdgcn_global_load_lds((const unsigned*)((const char*)(gbase) + (voff)[_i]), (LAS unsigned*)(lds + (bufoff) + ldsw + _i * 8192), 16, 0, 0); } while (0)
; #define PG8_LDA(dst, b, h) do { _Pragma("unroll") for (int m = 0; m < 4; ++m) _Pragma("unroll") for (int k = 0; k < 2; ++k) dst[m][k] = *(const LAS bf16x8*)(lds + PG8_SA(b, h) + aoff + m * 2048 + k * 1024); } while (0)
; #define PG8_LDB(dst, b, h) do { _Pragma("unroll") for (int n = 0; n < 2; ++n) _Pragma("unroll") for (int k = 0; k < 2; ++k) dst[n][k] = *(const LAS bf16x8*)(lds + PG8_SB(b, h) + boff + n * 2048 + k * 1024); } while (0)
; #define PG8_BAR __builtin_amdgcn_s_barrier()
; template <class Sched, class Epi, bool ALIGN_EPI, bool SP2>
; __device__ __forceinline__ void gemm_phase(LAS unsigned char* lds, const int K, const int lda, const int ldb, const Sched& S, const Epi& E) {
;     ...
;         for (int t = 0; t < nt; t += 2) {
;             const bool last = (t == nt - 2);
;             const char* a1 = cA + (size_t)(t + 1) * kstep;
;             const char* a2 = last ? nA : cA + (size_t)(t + 2) * kstep; const char* b2 = last ? nB : cB + (size_t)(t + 2) * kstep;
;             const char* a3 = a2 + kstep; const char* b3 = b2 + kstep;
;             if constexpr (SP2) {
;             PG8_LDB(B0, 0, 0); PG8_LDB(B1, 0, 1); PG8_SCHED; PG8_LDA(At, 0, 0); PG8_STAGE(PG8_SA(1, 1), a1 + hstepA, voffA);
;             PG8_WAIT_V(8); PG8_WAIT_L(0); PG8_BAR; PG8_MMA(0, 0, At, B0); PG8_MMA(0, 1, At, B1); PG8_BAR; PG8_SCHED;
;             PG8_LDA(At, 0, 1); PG8_STAGE(PG8_SB(0, 0), b2, voffB); PG8_STAGE(PG8_SB(0, 1), b2 + hstepB, voffB); PG8_STAGE(PG8_SA(0, 0), a2, voffA);
;             PG8_WAIT_V(8); PG8_WAIT_L(0); PG8_BAR; PG8_MMA(1, 0, At, B0); PG8_MMA(1, 1, At, B1); PG8_BAR; PG8_SCHED;
;             PG8_LDB(B0, 1, 0); PG8_LDB(B1, 1, 1); PG8_SCHED; PG8_LDA(At, 1, 0); PG8_STAGE(PG8_SA(0, 1), a2 + hstepA, voffA);
;             PG8_WAIT_V(8); PG8_WAIT_L(0); PG8_BAR; PG8_MMA(0, 0, At, B0); PG8_MMA(0, 1, At, B1); PG8_BAR; PG8_SCHED;
;             PG8_LDA(At, 1, 1); PG8_STAGE(PG8_SB(1, 0), b3, voffB); PG8_STAGE(PG8_SB(1, 1), b3 + hstepB, voffB); PG8_STAGE(PG8_SA(1, 0), a3, voffA);
;             PG8_WAIT_V(8); PG8_WAIT_L(0); PG8_BAR; PG8_MMA(1, 0, At, B0); PG8_MMA(1, 1, At, B1); PG8_BAR; PG8_SCHED;
	s_add_i32 s58, 0, 0x18000
	s_add_i32 s59, 0, 0x1c000
	v_add_u32_e32 v76, s58, v181
	v_add_u32_e32 v168, s59, v181
	ds_read_b128 v[64:67], v76
	ds_read_b128 v[68:71], v76 offset:1024
	ds_read_b128 v[72:75], v76 offset:2048
	ds_read_b128 v[76:79], v76 offset:3072
	ds_read_b128 v[144:147], v168
	ds_read_b128 v[160:163], v168 offset:1024
	ds_read_b128 v[164:167], v168 offset:2048
	ds_read_b128 v[168:171], v168 offset:3072
	s_add_u32 s44, s44, 0x80000
	s_addc_u32 s45, s45, 0
	s_mov_b32 m0, s46
	ds_read_b128 v[172:175], v185 offset:32768
	ds_read_b128 v[188:191], v185 offset:33792
	ds_read_b128 v[192:195], v185 offset:34816
	ds_read_b128 v[196:199], v185 offset:35840
	ds_read_b128 v[200:203], v185 offset:36864
	ds_read_b128 v[204:207], v185 offset:37888
	ds_read_b128 v[208:211], v185 offset:38912
	ds_read_b128 v[212:215], v185 offset:39936
	global_load_lds_dwordx4 v148, s[44:45]
	s_mov_b32 m0, s47
	s_nop 0
	global_load_lds_dwordx4 v152, s[44:45]
	s_waitcnt vmcnt(8) lgkmcnt(0)
	s_barrier
	v_mfma_f32_16x16x32_bf16 v[140:143], v[64:67], v[172:175], v[140:143]
	v_mfma_f32_16x16x32_bf16 v[136:139], v[72:75], v[172:175], v[136:139]
	v_mfma_f32_16x16x32_bf16 v[124:127], v[64:67], v[192:195], v[124:127]
	v_mfma_f32_16x16x32_bf16 v[120:123], v[72:75], v[192:195], v[120:123]
	v_mfma_f32_16x16x32_bf16 v[108:111], v[64:67], v[200:203], v[108:111]
	v_mfma_f32_16x16x32_bf16 v[104:107], v[72:75], v[200:203], v[104:107]
	v_mfma_f32_16x16x32_bf16 v[92:95], v[64:67], v[208:211], v[92:95]
	v_mfma_f32_16x16x32_bf16 v[88:91], v[72:75], v[208:211], v[88:91]
	v_mfma_f32_16x16x32_bf16 v[140:143], v[68:71], v[188:191], v[140:143]
	v_mfma_f32_16x16x32_bf16 v[136:139], v[76:79], v[188:191], v[136:139]
	v_mfma_f32_16x16x32_bf16 v[124:127], v[68:71], v[196:199], v[124:127]
	v_mfma_f32_16x16x32_bf16 v[120:123], v[76:79], v[196:199], v[120:123]
	v_mfma_f32_16x16x32_bf16 v[108:111], v[68:71], v[204:207], v[108:111]
	v_mfma_f32_16x16x32_bf16 v[104:107], v[76:79], v[204:207], v[104:107]
	v_mfma_f32_16x16x32_bf16 v[92:95], v[68:71], v[212:215], v[92:95]
	v_mfma_f32_16x16x32_bf16 v[88:91], v[76:79], v[212:215], v[88:91]
	v_mfma_f32_16x16x32_bf16 v[132:135], v[144:147], v[172:175], v[132:135]
	v_mfma_f32_16x16x32_bf16 v[128:131], v[164:167], v[172:175], v[128:131]
	v_mfma_f32_16x16x32_bf16 v[116:119], v[144:147], v[192:195], v[116:119]
	v_mfma_f32_16x16x32_bf16 v[112:115], v[164:167], v[192:195], v[112:115]
	v_mfma_f32_16x16x32_bf16 v[100:103], v[144:147], v[200:203], v[100:103]
	v_mfma_f32_16x16x32_bf16 v[96:99], v[164:167], v[200:203], v[96:99]
	v_mfma_f32_16x16x32_bf16 v[84:87], v[144:147], v[208:211], v[84:87]
	v_mfma_f32_16x16x32_bf16 v[80:83], v[164:167], v[208:211], v[80:83]
	v_mfma_f32_16x16x32_bf16 v[132:135], v[160:163], v[188:191], v[132:135]
	v_mfma_f32_16x16x32_bf16 v[128:131], v[168:171], v[188:191], v[128:131]
	v_mfma_f32_16x16x32_bf16 v[116:119], v[160:163], v[196:199], v[116:119]
	v_mfma_f32_16x16x32_bf16 v[112:115], v[168:171], v[196:199], v[112:115]
	v_mfma_f32_16x16x32_bf16 v[100:103], v[160:163], v[204:207], v[100:103]
	v_mfma_f32_16x16x32_bf16 v[96:99], v[168:171], v[204:207], v[96:99]
	v_mfma_f32_16x16x32_bf16 v[84:87], v[160:163], v[212:215], v[84:87]
	v_mfma_f32_16x16x32_bf16 v[80:83], v[168:171], v[212:215], v[80:83]
	s_barrier
	s_add_i32 s44, s58, s21
	v_lshl_add_u64 v[216:217], v[216:217], 0, s[14:15]
	s_mov_b32 m0, s44
	ds_read_b128 v[172:175], v185 offset:49152
	ds_read_b128 v[188:191], v185 offset:50176
	ds_read_b128 v[192:195], v185 offset:51200
	ds_read_b128 v[196:199], v185 offset:52224
	ds_read_b128 v[200:203], v185 offset:53248
	ds_read_b128 v[204:207], v185 offset:54272
	ds_read_b128 v[208:211], v185 offset:55296
	ds_read_b128 v[212:215], v185 offset:56320
	global_load_lds_dwordx4 v[216:217], off
	s_add_i32 m0, s44, 0x2000
	s_add_u32 s42, s42, 0x80080
	v_lshl_add_u64 v[216:217], v[218:219], 0, s[14:15]
	s_addc_u32 s43, s43, 0
	s_add_i32 s44, s59, s21
	global_load_lds_dwordx4 v[216:217], off
	s_mov_b32 m0, s44
	s_nop 0
	global_load_lds_dwordx4 v150, s[42:43]
	s_add_i32 m0, s44, 0x2000
	s_nop 0
	global_load_lds_dwordx4 v154, s[42:43]
	v_lshl_add_u64 v[216:217], v[220:221], 0, s[14:15]
	s_mov_b32 m0, s49
	s_nop 0
	global_load_lds_dwordx4 v[216:217], off
	v_lshl_add_u64 v[216:217], v[222:223], 0, s[14:15]
	s_mov_b32 m0, s50
	s_nop 0
	global_load_lds_dwordx4 v[216:217], off
	s_waitcnt vmcnt(8) lgkmcnt(0)
	s_barrier
	v_mfma_f32_16x16x32_bf16 v[60:63], v[64:67], v[172:175], v[60:63]
	v_mfma_f32_16x16x32_bf16 v[56:59], v[72:75], v[172:175], v[56:59]
	v_mfma_f32_16x16x32_bf16 v[44:47], v[64:67], v[192:195], v[44:47]
	v_mfma_f32_16x16x32_bf16 v[40:43], v[72:75], v[192:195], v[40:43]
	v_mfma_f32_16x16x32_bf16 v[24:27], v[64:67], v[200:203], v[24:27]
	v_mfma_f32_16x16x32_bf16 v[20:23], v[72:75], v[200:203], v[20:23]
	v_mfma_f32_16x16x32_bf16 v[8:11], v[64:67], v[208:211], v[8:11]
	v_mfma_f32_16x16x32_bf16 v[0:3], v[72:75], v[208:211], v[0:3]
	v_mfma_f32_16x16x32_bf16 v[60:63], v[68:71], v[188:191], v[60:63]
	v_mfma_f32_16x16x32_bf16 v[56:59], v[76:79], v[188:191], v[56:59]
	v_mfma_f32_16x16x32_bf16 v[44:47], v[68:71], v[196:199], v[44:47]
	v_mfma_f32_16x16x32_bf16 v[40:43], v[76:79], v[196:199], v[40:43]
	v_mfma_f32_16x16x32_bf16 v[24:27], v[68:71], v[204:207], v[24:27]
	v_mfma_f32_16x16x32_bf16 v[20:23], v[76:79], v[204:207], v[20:23]
	v_mfma_f32_16x16x32_bf16 v[8:11], v[68:71], v[212:215], v[8:11]
	v_mfma_f32_16x16x32_bf16 v[0:3], v[76:79], v[212:215], v[0:3]
	v_mfma_f32_16x16x32_bf16 v[52:55], v[144:147], v[172:175], v[52:55]
	v_mfma_f32_16x16x32_bf16 v[48:51], v[164:167], v[172:175], v[48:51]
	v_mfma_f32_16x16x32_bf16 v[36:39], v[144:147], v[192:195], v[36:39]
	v_mfma_f32_16x16x32_bf16 v[32:35], v[164:167], v[192:195], v[32:35]
	v_mfma_f32_16x16x32_bf16 v[28:31], v[144:147], v[200:203], v[28:31]
	v_mfma_f32_16x16x32_bf16 v[16:19], v[164:167], v[200:203], v[16:19]
	v_mfma_f32_16x16x32_bf16 v[12:15], v[144:147], v[208:211], v[12:15]
	v_mfma_f32_16x16x32_bf16 v[4:7], v[164:167], v[208:211], v[4:7]
	v_mfma_f32_16x16x32_bf16 v[52:55], v[160:163], v[188:191], v[52:55]
	v_mfma_f32_16x16x32_bf16 v[48:51], v[168:171], v[188:191], v[48:51]
	v_mfma_f32_16x16x32_bf16 v[36:39], v[160:163], v[196:199], v[36:39]
	v_mfma_f32_16x16x32_bf16 v[32:35], v[168:171], v[196:199], v[32:35]
	v_mfma_f32_16x16x32_bf16 v[28:31], v[160:163], v[204:207], v[28:31]
	v_mfma_f32_16x16x32_bf16 v[16:19], v[168:171], v[204:207], v[16:19]
	v_mfma_f32_16x16x32_bf16 v[12:15], v[160:163], v[212:215], v[12:15]
	v_mfma_f32_16x16x32_bf16 v[4:7], v[168:171], v[212:215], v[4:7]
	s_barrier
	s_add_i32 s57, s57, 2
	s_add_u32 s36, s36, 0x100
	s_addc_u32 s37, s37, 0
	s_add_u32 s25, s25, 0x100
	s_addc_u32 s56, s56, 0
	s_cmp_gt_u32 s57, 29

; #define PG8_STAGE(bufoff, gbase, voff) do { _Pragma("unroll") for (int _i = 0; _i < 2; ++_i) \
;         __builtin_amdgcn_global_load_lds((const unsigned*)((const char*)(gbase) + (voff)[_i]), (LAS unsigned*)(lds + (bufoff) + ldsw + _i * 8192), 16, 0, 0); } while (0)
; #define PG8_LDA(dst, b, h) do { _Pragma("unroll") for (int m = 0; m < 4; ++m) _Pragma("unroll") for (int k = 0; k < 2; ++k) dst[m][k] = *(const LAS bf16x8*)(lds + PG8_SA(b, h) + aoff + m * 2048 + k * 1024); } while (0)
; #define PG8_LDB(dst, b, h) do { _Pragma("unroll") for (int n = 0; n < 2; ++n) _Pragma("unroll") for (int k = 0; k < 2; ++k) dst[n][k] = *(const LAS bf16x8*)(lds + PG8_SB(b, h) + boff + n * 2048 + k * 1024); } while (0)
; #define PG8_WAIT_V(n) asm volatile("s_waitcnt vmcnt(" #n ")" ::: "memory")
; template <class Sched, class Epi, bool ALIGN_EPI, bool SP2>
; __device__ __forceinline__ void gemm_phase(LAS unsigned char* lds, const int K, const int lda, const int ldb, const Sched& S, const Epi& E) {
;     ...
;         const bool has_next = S.next(ui + 1, nxt);
;         const char* nA = has_next ? nxt.A : cA; const char* nB = has_next ? nxt.B : cB;
;         for (int t = 0; t < nt; t += 2) {
;             const bool last = (t == nt - 2);
;             const char* a1 = cA + (size_t)(t + 1) * kstep;
;             const char* a2 = last ? nA : cA + (size_t)(t + 2) * kstep; const char* b2 = last ? nB : cB + (size_t)(t + 2) * kstep;
;             const char* a3 = a2 + kstep; const char* b3 = b2 + kstep;
;             if constexpr (SP2) {
;             PG8_LDB(B0, 0, 0); PG8_LDB(B1, 0, 1); PG8_SCHED; PG8_LDA(At, 0, 0); PG8_STAGE(PG8_SA(1, 1), a1 + hstepA, voffA);
;             PG8_WAIT_V(8); PG8_WAIT_L(0); PG8_BAR; PG8_MMA(0, 0, At, B0); PG8_MMA(0, 1, At, B1); PG8_BAR; PG8_SCHED;
;             PG8_LDA(At, 0, 1); PG8_STAGE(PG8_SB(0, 0), b2, voffB); PG8_STAGE(PG8_SB(0, 1), b2 + hstepB, voffB); PG8_STAGE(PG8_SA(0, 0), a2, voffA);
;             PG8_WAIT_V(8); PG8_WAIT_L(0); PG8_BAR; PG8_MMA(1, 0, At, B0); PG8_MMA(1, 1, At, B1); PG8_BAR; PG8_SCHED;
;     ...
;         if (!keep) {
; #pragma unroll
;         for (int a = 0; a < 2; ++a)
; #pragma unroll
;             for (int b = 0; b < 2; ++b)
; #pragma unroll
;                 for (int m = 0; m < 4; ++m)
; #pragma unroll
;                     for (int n = 0; n < 2; ++n) acc[a][b][m][n] = (f32x4){0.f, 0.f, 0.f, 0.f};
;         }
.LBB0_1119:
	s_add_u32 s49, s4, 0x100
	v_mov_b32_e32 v0, 0
	s_addc_u32 s50, s5, 0
	s_mov_b32 s51, -2
	v_readlane_b32 s98, v255, 13
	s_nop 4
	s_cmp_gt_u32 s98, 3
	s_cbranch_scc1 .Lprio_skip_1120
	s_setprio 1
.Lprio_skip_1120:
	ds_read_b128 v[96:99], v178
	ds_read_b128 v[100:103], v178 offset:1024
	ds_read_b128 v[104:107], v178 offset:2048
	ds_read_b128 v[108:111], v178 offset:3072
	ds_read_b128 v[112:115], v180
	ds_read_b128 v[116:119], v180 offset:1024
	ds_read_b128 v[120:123], v180 offset:2048
	ds_read_b128 v[124:127], v180 offset:3072
	s_add_u32 s4, s0, 0x100
	s_addc_u32 s5, s1, 0
	s_cmpk_eq_i32 s51, 0x54
	s_cselect_b32 s27, s21, s5
	s_cselect_b32 s26, s20, s4
	s_cselect_b32 s25, s23, s50
	s_cselect_b32 s24, s22, s49
	s_add_i32 m0, s17, 0xc000
	ds_read_b128 v[168:171], v181
	ds_read_b128 v[184:187], v181 offset:1024
	ds_read_b128 v[188:191], v181 offset:2048
	ds_read_b128 v[192:195], v181 offset:3072
	ds_read_b128 v[196:199], v181 offset:4096
	ds_read_b128 v[200:203], v181 offset:5120
	ds_read_b128 v[204:207], v181 offset:6144
	ds_read_b128 v[208:211], v181 offset:7168
	global_load_lds_dwordx4 v164, s[0:1]
	s_add_i32 m0, s17, 0xe000
	s_nop 0
	global_load_lds_dwordx4 v166, s[0:1]
	s_waitcnt vmcnt(8) lgkmcnt(0)
	s_barrier
	v_mfma_f32_16x16x32_bf16 v[156:159], v[96:99], v[168:171], 0
	v_mfma_f32_16x16x32_bf16 v[152:155], v[104:107], v[168:171], 0
	v_mfma_f32_16x16x32_bf16 v[144:147], v[96:99], v[188:191], 0
	v_mfma_f32_16x16x32_bf16 v[136:139], v[104:107], v[188:191], 0
	v_mfma_f32_16x16x32_bf16 v[92:95], v[96:99], v[196:199], 0
	v_mfma_f32_16x16x32_bf16 v[88:91], v[104:107], v[196:199], 0
	v_mfma_f32_16x16x32_bf16 v[80:83], v[96:99], v[204:207], 0
	v_mfma_f32_16x16x32_bf16 v[72:75], v[104:107], v[204:207], 0
	v_mfma_f32_16x16x32_bf16 v[156:159], v[100:103], v[184:187], v[156:159]
	v_mfma_f32_16x16x32_bf16 v[152:155], v[108:111], v[184:187], v[152:155]
	v_mfma_f32_16x16x32_bf16 v[144:147], v[100:103], v[192:195], v[144:147]
	v_mfma_f32_16x16x32_bf16 v[136:139], v[108:111], v[192:195], v[136:139]
	v_mfma_f32_16x16x32_bf16 v[92:95], v[100:103], v[200:203], v[92:95]
	v_mfma_f32_16x16x32_bf16 v[88:91], v[108:111], v[200:203], v[88:91]
	v_mfma_f32_16x16x32_bf16 v[80:83], v[100:103], v[208:211], v[80:83]
	v_mfma_f32_16x16x32_bf16 v[72:75], v[108:111], v[208:211], v[72:75]
	v_mfma_f32_16x16x32_bf16 v[148:151], v[112:115], v[168:171], 0
	v_mfma_f32_16x16x32_bf16 v[140:143], v[120:123], v[168:171], 0
	v_mfma_f32_16x16x32_bf16 v[132:135], v[112:115], v[188:191], 0
	v_mfma_f32_16x16x32_bf16 v[128:131], v[120:123], v[188:191], 0
	v_mfma_f32_16x16x32_bf16 v[84:87], v[112:115], v[196:199], 0
	v_mfma_f32_16x16x32_bf16 v[76:79], v[120:123], v[196:199], 0
	v_mfma_f32_16x16x32_bf16 v[68:71], v[112:115], v[204:207], 0
	v_mfma_f32_16x16x32_bf16 v[64:67], v[120:123], v[204:207], 0
	v_mfma_f32_16x16x32_bf16 v[148:151], v[116:119], v[184:187], v[148:151]
	v_mfma_f32_16x16x32_bf16 v[140:143], v[124:127], v[184:187], v[140:143]
	v_mfma_f32_16x16x32_bf16 v[132:135], v[116:119], v[192:195], v[132:135]
	v_mfma_f32_16x16x32_bf16 v[128:131], v[124:127], v[192:195], v[128:131]
	v_mfma_f32_16x16x32_bf16 v[84:87], v[116:119], v[200:203], v[84:87]
	v_mfma_f32_16x16x32_bf16 v[76:79], v[124:127], v[200:203], v[76:79]
	v_mfma_f32_16x16x32_bf16 v[68:71], v[116:119], v[208:211], v[68:71]
	v_mfma_f32_16x16x32_bf16 v[64:67], v[124:127], v[208:211], v[64:67]
	s_barrier
	s_add_i32 s0, s42, s15
	v_lshl_add_u64 v[172:173], s[24:25], 0, v[160:161]
	s_mov_b32 m0, s0
	ds_read_b128 v[168:171], v181 offset:16384
	ds_read_b128 v[184:187], v181 offset:17408
	ds_read_b128 v[188:191], v181 offset:18432
	ds_read_b128 v[192:195], v181 offset:19456
	ds_read_b128 v[196:199], v181 offset:20480
	ds_read_b128 v[200:203], v181 offset:21504
	ds_read_b128 v[204:207], v181 offset:22528
	ds_read_b128 v[208:211], v181 offset:23552
	global_load_lds_dwordx4 v[172:173], off
	s_add_i32 m0, s0, 0x2000
	s_add_u32 s0, s24, 0x160000
	v_lshl_add_u64 v[212:213], s[24:25], 0, v[162:163]
	s_addc_u32 s1, s25, 0
	s_add_i32 s52, s43, s15
	global_load_lds_dwordx4 v[212:213], off
	s_mov_b32 m0, s52
	v_lshl_add_u64 v[216:217], s[26:27], 0, v[162:163]
	global_load_lds_dwordx4 v160, s[0:1]
	s_add_i32 m0, s52, 0x2000
	s_nop 0
	global_load_lds_dwordx4 v162, s[0:1]
	v_lshl_add_u64 v[214:215], s[26:27], 0, v[160:161]
	s_mov_b32 m0, s17
	s_nop 0
	global_load_lds_dwordx4 v[214:215], off
	s_mov_b32 m0, s28
	s_nop 0
	global_load_lds_dwordx4 v[216:217], off
	s_waitcnt vmcnt(8) lgkmcnt(0)
	s_barrier
	v_mfma_f32_16x16x32_bf16 v[60:63], v[96:99], v[168:171], 0
	v_mfma_f32_16x16x32_bf16 v[56:59], v[104:107], v[168:171], 0
	v_mfma_f32_16x16x32_bf16 v[48:51], v[96:99], v[188:191], 0
	v_mfma_f32_16x16x32_bf16 v[40:43], v[104:107], v[188:191], 0
	v_mfma_f32_16x16x32_bf16 v[28:31], v[96:99], v[196:199], 0
	v_mfma_f32_16x16x32_bf16 v[24:27], v[104:107], v[196:199], 0
	v_mfma_f32_16x16x32_bf16 v[16:19], v[96:99], v[204:207], 0
	v_mfma_f32_16x16x32_bf16 v[8:11], v[104:107], v[204:207], 0
	v_mfma_f32_16x16x32_bf16 v[60:63], v[100:103], v[184:187], v[60:63]
	v_mfma_f32_16x16x32_bf16 v[56:59], v[108:111], v[184:187], v[56:59]
	v_mfma_f32_16x16x32_bf16 v[48:51], v[100:103], v[192:195], v[48:51]
	v_mfma_f32_16x16x32_bf16 v[40:43], v[108:111], v[192:195], v[40:43]
	v_mfma_f32_16x16x32_bf16 v[28:31], v[100:103], v[200:203], v[28:31]
	v_mfma_f32_16x16x32_bf16 v[24:27], v[108:111], v[200:203], v[24:27]
	v_mfma_f32_16x16x32_bf16 v[16:19], v[100:103], v[208:211], v[16:19]
	v_mfma_f32_16x16x32_bf16 v[8:11], v[108:111], v[208:211], v[8:11]
	v_mfma_f32_16x16x32_bf16 v[52:55], v[112:115], v[168:171], 0
	v_mfma_f32_16x16x32_bf16 v[44:47], v[120:123], v[168:171], 0
	v_mfma_f32_16x16x32_bf16 v[36:39], v[112:115], v[188:191], 0
	v_mfma_f32_16x16x32_bf16 v[32:35], v[120:123], v[188:191], 0
	v_mfma_f32_16x16x32_bf16 v[20:23], v[112:115], v[196:199], 0
	v_mfma_f32_16x16x32_bf16 v[12:15], v[120:123], v[196:199], 0
	v_mfma_f32_16x16x32_bf16 v[4:7], v[112:115], v[204:207], 0
	v_mfma_f32_16x16x32_bf16 v[0:3], v[120:123], v[204:207], 0
	v_mfma_f32_16x16x32_bf16 v[52:55], v[116:119], v[184:187], v[52:55]
	v_mfma_f32_16x16x32_bf16 v[44:47], v[124:127], v[184:187], v[44:47]
	v_mfma_f32_16x16x32_bf16 v[36:39], v[116:119], v[192:195], v[36:39]
	v_mfma_f32_16x16x32_bf16 v[32:35], v[124:127], v[192:195], v[32:35]
	v_mfma_f32_16x16x32_bf16 v[20:23], v[116:119], v[200:203], v[20:23]
	v_mfma_f32_16x16x32_bf16 v[12:15], v[124:127], v[200:203], v[12:15]
	v_mfma_f32_16x16x32_bf16 v[4:7], v[116:119], v[208:211], v[4:7]
	v_mfma_f32_16x16x32_bf16 v[0:3], v[124:127], v[208:211], v[0:3]
	s_barrier
; #define PG8_STAGE(bufoff, gbase, voff) do { _Pragma("unroll") for (int _i = 0; _i < 2; ++_i) \
;         __builtin_amdgcn_global_load_lds((const unsigned*)((const char*)(gbase) + (voff)[_i]), (LAS unsigned*)(lds + (bufoff) + ldsw + _i * 8192), 16, 0, 0); } while (0)
; #define PG8_LDA(dst, b, h) do { _Pragma("unroll") for (int m = 0; m < 4; ++m) _Pragma("unroll") for (int k = 0; k < 2; ++k) dst[m][k] = *(const LAS bf16x8*)(lds + PG8_SA(b, h) + aoff + m * 2048 + k * 1024); } while (0)
; #define PG8_LDB(dst, b, h) do { _Pragma("unroll") for (int n = 0; n < 2; ++n) _Pragma("unroll") for (int k = 0; k < 2; ++k) dst[n][k] = *(const LAS bf16x8*)(lds + PG8_SB(b, h) + boff + n * 2048 + k * 1024); } while (0)
; #define PG8_MMA(ai, bj, At, Bt) do { __builtin_amdgcn_s_setprio(1); _Pragma("unroll") for (int m = 0; m < 4; ++m) _Pragma("unroll") for (int n = 0; n < 2; ++n) _Pragma("unroll") for (int k = 0; k < 2; ++k) \
;         acc[ai][bj][m][n] = __builtin_amdgcn_mfma_f32_16x16x32_bf16(Bt[n][k], At[m][k], acc[ai][bj][m][n], 0, 0, 0); __builtin_amdgcn_s_setprio(0); } while (0)
; #define PG8_WAIT_V(n) asm volatile("s_waitcnt vmcnt(" #n ")" ::: "memory")
; #define PG8_WAIT_L(n) asm volatile("s_waitcnt lgkmcnt(" #n ")" ::: "memory")
; #define PG8_BAR __builtin_amdgcn_s_barrier()
; template <class Sched, class Epi, bool ALIGN_EPI, bool SP2>
; __device__ __forceinline__ void gemm_phase(LAS unsigned char* lds, const int K, const int lda, const int ldb, const Sched& S, const Epi& E) {
;     ...
;         for (int t = 0; t < nt; t += 2) {
;             const bool last = (t == nt - 2);
;             const char* a1 = cA + (size_t)(t + 1) * kstep;
;             const char* a2 = last ? nA : cA + (size_t)(t + 2) * kstep; const char* b2 = last ? nB : cB + (size_t)(t + 2) * kstep;
;             const char* a3 = a2 + kstep; const char* b3 = b2 + kstep;
;     ...
;             PG8_LDB(B0, 1, 0); PG8_LDB(B1, 1, 1); PG8_SCHED; PG8_LDA(At, 1, 0); PG8_STAGE(PG8_SA(0, 1), a2 + hstepA, voffA);
;             PG8_WAIT_V(8); PG8_WAIT_L(0); PG8_BAR; PG8_MMA(0, 0, At, B0); PG8_MMA(0, 1, At, B1); PG8_BAR; PG8_SCHED;
;             PG8_LDA(At, 1, 1); PG8_STAGE(PG8_SB(1, 0), b3, voffB); PG8_STAGE(PG8_SB(1, 1), b3 + hstepB, voffB); PG8_STAGE(PG8_SA(1, 0), a3, voffA);
;             PG8_WAIT_V(8); PG8_WAIT_L(0); PG8_BAR; PG8_MMA(1, 0, At, B0); PG8_MMA(1, 1, At, B1); PG8_BAR; PG8_SCHED;
	s_add_i32 s52, 0, 0x18000
	s_add_i32 s53, 0, 0x1c000
	v_add_u32_e32 v108, s52, v175
	v_add_u32_e32 v124, s53, v175
	ds_read_b128 v[96:99], v108
	ds_read_b128 v[100:103], v108 offset:1024
	ds_read_b128 v[104:107], v108 offset:2048
	ds_read_b128 v[108:111], v108 offset:3072
	ds_read_b128 v[112:115], v124
	ds_read_b128 v[116:119], v124 offset:1024
	ds_read_b128 v[120:123], v124 offset:2048
	ds_read_b128 v[124:127], v124 offset:3072
	s_add_u32 s0, s26, 0x160000
	s_addc_u32 s1, s27, 0
	s_mov_b32 m0, s29
	ds_read_b128 v[168:171], v181 offset:32768
	ds_read_b128 v[184:187], v181 offset:33792
	ds_read_b128 v[188:191], v181 offset:34816
	ds_read_b128 v[192:195], v181 offset:35840
	ds_read_b128 v[196:199], v181 offset:36864
	ds_read_b128 v[200:203], v181 offset:37888
	ds_read_b128 v[204:207], v181 offset:38912
	ds_read_b128 v[208:211], v181 offset:39936
	global_load_lds_dwordx4 v160, s[0:1]
	s_mov_b32 m0, s33
	s_nop 0
	global_load_lds_dwordx4 v162, s[0:1]
	s_waitcnt vmcnt(8) lgkmcnt(0)
	s_barrier
	v_mfma_f32_16x16x32_bf16 v[156:159], v[96:99], v[168:171], v[156:159]
	v_mfma_f32_16x16x32_bf16 v[152:155], v[104:107], v[168:171], v[152:155]
	v_mfma_f32_16x16x32_bf16 v[144:147], v[96:99], v[188:191], v[144:147]
	v_mfma_f32_16x16x32_bf16 v[136:139], v[104:107], v[188:191], v[136:139]
	v_mfma_f32_16x16x32_bf16 v[92:95], v[96:99], v[196:199], v[92:95]
	v_mfma_f32_16x16x32_bf16 v[88:91], v[104:107], v[196:199], v[88:91]
	v_mfma_f32_16x16x32_bf16 v[80:83], v[96:99], v[204:207], v[80:83]
	v_mfma_f32_16x16x32_bf16 v[72:75], v[104:107], v[204:207], v[72:75]
	v_mfma_f32_16x16x32_bf16 v[156:159], v[100:103], v[184:187], v[156:159]
	v_mfma_f32_16x16x32_bf16 v[152:155], v[108:111], v[184:187], v[152:155]
	v_mfma_f32_16x16x32_bf16 v[144:147], v[100:103], v[192:195], v[144:147]
	v_mfma_f32_16x16x32_bf16 v[136:139], v[108:111], v[192:195], v[136:139]
	v_mfma_f32_16x16x32_bf16 v[92:95], v[100:103], v[200:203], v[92:95]
	v_mfma_f32_16x16x32_bf16 v[88:91], v[108:111], v[200:203], v[88:91]
	v_mfma_f32_16x16x32_bf16 v[80:83], v[100:103], v[208:211], v[80:83]
	v_mfma_f32_16x16x32_bf16 v[72:75], v[108:111], v[208:211], v[72:75]
	v_mfma_f32_16x16x32_bf16 v[148:151], v[112:115], v[168:171], v[148:151]
	v_mfma_f32_16x16x32_bf16 v[140:143], v[120:123], v[168:171], v[140:143]
	v_mfma_f32_16x16x32_bf16 v[132:135], v[112:115], v[188:191], v[132:135]
	v_mfma_f32_16x16x32_bf16 v[128:131], v[120:123], v[188:191], v[128:131]
	v_mfma_f32_16x16x32_bf16 v[84:87], v[112:115], v[196:199], v[84:87]
	v_mfma_f32_16x16x32_bf16 v[76:79], v[120:123], v[196:199], v[76:79]
	v_mfma_f32_16x16x32_bf16 v[68:71], v[112:115], v[204:207], v[68:71]
	v_mfma_f32_16x16x32_bf16 v[64:67], v[120:123], v[204:207], v[64:67]
	v_mfma_f32_16x16x32_bf16 v[148:151], v[116:119], v[184:187], v[148:151]
	v_mfma_f32_16x16x32_bf16 v[140:143], v[124:127], v[184:187], v[140:143]
	v_mfma_f32_16x16x32_bf16 v[132:135], v[116:119], v[192:195], v[132:135]
	v_mfma_f32_16x16x32_bf16 v[128:131], v[124:127], v[192:195], v[128:131]
	v_mfma_f32_16x16x32_bf16 v[84:87], v[116:119], v[200:203], v[84:87]
	v_mfma_f32_16x16x32_bf16 v[76:79], v[124:127], v[200:203], v[76:79]
	v_mfma_f32_16x16x32_bf16 v[68:71], v[116:119], v[208:211], v[68:71]
	v_mfma_f32_16x16x32_bf16 v[64:67], v[124:127], v[208:211], v[64:67]
	s_barrier
	s_add_i32 s0, s52, s15
	v_lshl_add_u64 v[172:173], v[172:173], 0, s[10:11]
	s_mov_b32 m0, s0
	ds_read_b128 v[168:171], v181 offset:49152
	ds_read_b128 v[184:187], v181 offset:50176
	ds_read_b128 v[188:191], v181 offset:51200
	ds_read_b128 v[192:195], v181 offset:52224
	ds_read_b128 v[196:199], v181 offset:53248
	ds_read_b128 v[200:203], v181 offset:54272
	ds_read_b128 v[204:207], v181 offset:55296
	ds_read_b128 v[208:211], v181 offset:56320
	global_load_lds_dwordx4 v[172:173], off
	s_add_i32 m0, s0, 0x2000
	s_add_u32 s0, s24, 0x160080
	v_lshl_add_u64 v[172:173], v[212:213], 0, s[10:11]
	s_addc_u32 s1, s25, 0
	s_add_i32 s24, s53, s15
	global_load_lds_dwordx4 v[172:173], off
	s_mov_b32 m0, s24
	s_nop 0
	global_load_lds_dwordx4 v160, s[0:1]
	s_add_i32 m0, s24, 0x2000
	s_nop 0
	global_load_lds_dwordx4 v162, s[0:1]
	v_lshl_add_u64 v[172:173], v[214:215], 0, s[10:11]
	s_mov_b32 m0, s36
	s_nop 0
	global_load_lds_dwordx4 v[172:173], off
	v_lshl_add_u64 v[172:173], v[216:217], 0, s[10:11]
	s_mov_b32 m0, s37
	s_nop 0
	global_load_lds_dwordx4 v[172:173], off
	s_waitcnt vmcnt(8) lgkmcnt(0)
	s_barrier
	v_mfma_f32_16x16x32_bf16 v[60:63], v[96:99], v[168:171], v[60:63]
	v_mfma_f32_16x16x32_bf16 v[56:59], v[104:107], v[168:171], v[56:59]
	v_mfma_f32_16x16x32_bf16 v[48:51], v[96:99], v[188:191], v[48:51]
	v_mfma_f32_16x16x32_bf16 v[40:43], v[104:107], v[188:191], v[40:43]
	v_mfma_f32_16x16x32_bf16 v[28:31], v[96:99], v[196:199], v[28:31]
	v_mfma_f32_16x16x32_bf16 v[24:27], v[104:107], v[196:199], v[24:27]
	v_mfma_f32_16x16x32_bf16 v[16:19], v[96:99], v[204:207], v[16:19]
	v_mfma_f32_16x16x32_bf16 v[8:11], v[104:107], v[204:207], v[8:11]
	v_mfma_f32_16x16x32_bf16 v[60:63], v[100:103], v[184:187], v[60:63]
	v_mfma_f32_16x16x32_bf16 v[56:59], v[108:111], v[184:187], v[56:59]
	v_mfma_f32_16x16x32_bf16 v[48:51], v[100:103], v[192:195], v[48:51]
	v_mfma_f32_16x16x32_bf16 v[40:43], v[108:111], v[192:195], v[40:43]
	v_mfma_f32_16x16x32_bf16 v[28:31], v[100:103], v[200:203], v[28:31]
	v_mfma_f32_16x16x32_bf16 v[24:27], v[108:111], v[200:203], v[24:27]
	v_mfma_f32_16x16x32_bf16 v[16:19], v[100:103], v[208:211], v[16:19]
	v_mfma_f32_16x16x32_bf16 v[8:11], v[108:111], v[208:211], v[8:11]
	v_mfma_f32_16x16x32_bf16 v[52:55], v[112:115], v[168:171], v[52:55]
	v_mfma_f32_16x16x32_bf16 v[44:47], v[120:123], v[168:171], v[44:47]
	v_mfma_f32_16x16x32_bf16 v[36:39], v[112:115], v[188:191], v[36:39]
	v_mfma_f32_16x16x32_bf16 v[32:35], v[120:123], v[188:191], v[32:35]
	v_mfma_f32_16x16x32_bf16 v[20:23], v[112:115], v[196:199], v[20:23]
	v_mfma_f32_16x16x32_bf16 v[12:15], v[120:123], v[196:199], v[12:15]
	v_mfma_f32_16x16x32_bf16 v[4:7], v[112:115], v[204:207], v[4:7]
	v_mfma_f32_16x16x32_bf16 v[0:3], v[120:123], v[204:207], v[0:3]
	v_mfma_f32_16x16x32_bf16 v[52:55], v[116:119], v[184:187], v[52:55]
	v_mfma_f32_16x16x32_bf16 v[44:47], v[124:127], v[184:187], v[44:47]
	v_mfma_f32_16x16x32_bf16 v[36:39], v[116:119], v[192:195], v[36:39]
	v_mfma_f32_16x16x32_bf16 v[32:35], v[124:127], v[192:195], v[32:35]
	v_mfma_f32_16x16x32_bf16 v[20:23], v[116:119], v[200:203], v[20:23]
	v_mfma_f32_16x16x32_bf16 v[12:15], v[124:127], v[200:203], v[12:15]
	v_mfma_f32_16x16x32_bf16 v[4:7], v[116:119], v[208:211], v[4:7]
	v_mfma_f32_16x16x32_bf16 v[0:3], v[124:127], v[208:211], v[0:3]
	s_barrier
	s_add_i32 s51, s51, 2
	s_add_u32 s49, s49, 0x100
	s_addc_u32 s50, s50, 0
	s_cmpk_gt_u32 s51, 0x55
	s_mov_b64 s[0:1], s[4:5]
